# LRU gates: bias pre-scaled so bias+scale is one fma, log2(e) folded into the per-channel decay constant; GLA gate log-sigmoid: ln(x) = log2(x)*ln2 with a single f32 multiply (compensated tail of logf
# speedup vs baseline: 1.0156x; 1.0030x over previous
; template <int DIR> __device__ __forceinline__ void lru_dir(const Params& p, int l, int n, int h, int lane, LAS bf16_t* XC, LAS float* STA, LAS float* STU) {
;     ...
;         const f32x4 lam4 = *(const f32x4*)(lam + 16 * nf + 4 * q); ba4[nf] = *(const f32x4*)(b_a + 16 * nf + 4 * q); bx4[nf] = *(const f32x4*)(b_x + 16 * nf + 4 * q);
; #pragma unroll
;         for (int r = 0; r < 4; ++r) { const float e = __expf(-lam4[r]); const float l1p = e < 0.05f ? e * (1.0f - e * (0.5f - e * (0.33333334f - e * 0.25f))) : __logf(1.0f + e); sp4[nf][r] = -8.0f * l1p; }
;     }
;     ...
;             const f32x4 zav = za[nf] + ba4[nf], zxv = zx[nf] + bx4[nf];
.LBB0_254:
	s_andn2_saveexec_b64 s[0:1], s[30:31]
	v_fmamk_f32 v99, v118, 0xbe800000, v226
	v_fma_f32 v99, -v118, v99, 0.5
	v_fma_f32 v99, -v118, v99, 1.0
	v_mul_f32_e32 v99, v118, v99
	s_or_b64 exec, exec, s[0:1]
	s_movk_i32 s0, 0x2200
	v_bfe_u32 v128, v100, 4, 2
	v_mul_f32_e32 v136, 0xc138aa3b, v96
	v_mul_lo_u32 v96, v102, s0
	v_readlane_b32 s0, v254, 23
	s_ashr_i32 s29, s28, 31
	v_and_b32_e32 v126, 63, v100
	v_lshlrev_b32_e32 v132, 2, v128
	v_mul_f32_e32 v135, 0xc138aa3b, v97
	v_add_u32_e32 v96, s0, v96
	v_mul_u32_u24_e32 v97, 0x44, v127
	s_lshl_b64 s[0:1], s[28:29], 11
	v_lshlrev_b64 v[118:119], 1, v[124:125]
	v_mul_f32_e32 v137, 0xc138aa3b, v117
	v_mul_f32_e32 v138, 0xc138aa3b, v116
	v_lshlrev_b32_e32 v97, 2, v97
	v_lshlrev_b32_e32 v120, 2, v132
	v_lshl_add_u64 v[116:117], s[0:1], 0, v[118:119]
	v_lshlrev_b32_e32 v176, 1, v126
	v_add3_u32 v154, v96, v97, v120
	v_lshl_add_u32 v155, v126, 2, v96
	v_lshl_add_u64 v[96:97], v[116:117], 0, v[176:177]
	v_lshl_add_u64 v[122:123], s[56:57], 0, v[96:97]
	v_lshlrev_b32_e32 v96, 1, v100
	v_and_b32_e32 v96, 0xffffff80, v96
	v_lshlrev_b32_e32 v133, 3, v128
	v_mad_u32_u24 v96, v127, s7, v96
	v_lshlrev_b32_e32 v97, 4, v128
	v_lshlrev_b32_e32 v121, 6, v127
	v_mul_f32_e32 v134, 0xc138aa3b, v98
	v_mul_f32_e32 v139, 0xc138aa3b, v111
	v_mul_f32_e32 v140, 0xc138aa3b, v110
	v_mul_f32_e32 v141, 0xc138aa3b, v109
	v_mul_f32_e32 v142, 0xc138aa3b, v108
	v_mul_f32_e32 v143, 0xc138aa3b, v107
	v_mul_f32_e32 v144, 0xc138aa3b, v106
	v_mul_f32_e32 v145, 0xc138aa3b, v105
	v_mul_f32_e32 v146, 0xc138aa3b, v104
	v_mul_f32_e32 v147, 0xc138aa3b, v103
	v_mul_f32_e32 v148, 0xc138aa3b, v101
	v_mul_f32_e32 v149, 0xc138aa3b, v99
	v_add3_u32 v150, v96, v97, 0
	v_add3_u32 v151, v96, v133, 0
	v_mov_b32_e32 v129, 1.0
	v_mov_b32_e32 v130, 0
	s_mov_b64 s[0:1], 0
	s_waitcnt vmcnt(0)
	s_lshl_b32 s64, s28, 11
	s_add_u32 s66, s56, s64
	s_addc_u32 s67, s57, 0
	s_add_u32 s66, s66, 0x1859000
	s_addc_u32 s67, s67, 0
	v_lshlrev_b32_e32 v220, 1, v245
	v_mul_f32_e32 v16, 0xbfb8aa3b, v16
	v_mul_f32_e32 v17, 0xbfb8aa3b, v17
	v_mul_f32_e32 v18, 0xbfb8aa3b, v18
	v_mul_f32_e32 v19, 0xbfb8aa3b, v19
	v_mul_f32_e32 v20, 0xbfb8aa3b, v20
	v_mul_f32_e32 v21, 0xbfb8aa3b, v21
	v_mul_f32_e32 v22, 0xbfb8aa3b, v22
	v_mul_f32_e32 v23, 0xbfb8aa3b, v23
	v_mul_f32_e32 v40, 0xbfb8aa3b, v40
	v_mul_f32_e32 v41, 0xbfb8aa3b, v41
	v_mul_f32_e32 v42, 0xbfb8aa3b, v42
	v_mul_f32_e32 v43, 0xbfb8aa3b, v43
	v_mul_f32_e32 v44, 0xbfb8aa3b, v44
	v_mul_f32_e32 v45, 0xbfb8aa3b, v45
	v_mul_f32_e32 v46, 0xbfb8aa3b, v46
	v_mul_f32_e32 v47, 0xbfb8aa3b, v47
	v_mul_f32_e32 v64, 0xbfb8aa3b, v64
	v_mul_f32_e32 v65, 0xbfb8aa3b, v65
	v_mul_f32_e32 v66, 0xbfb8aa3b, v66
	v_mul_f32_e32 v67, 0xbfb8aa3b, v67
	v_mul_f32_e32 v68, 0xbfb8aa3b, v68
	v_mul_f32_e32 v69, 0xbfb8aa3b, v69
	v_mul_f32_e32 v70, 0xbfb8aa3b, v70
	v_mul_f32_e32 v71, 0xbfb8aa3b, v71
	v_mul_f32_e32 v88, 0xbfb8aa3b, v88
	v_mul_f32_e32 v89, 0xbfb8aa3b, v89
	v_mul_f32_e32 v90, 0xbfb8aa3b, v90
	v_mul_f32_e32 v91, 0xbfb8aa3b, v91
	v_mul_f32_e32 v92, 0xbfb8aa3b, v92
	v_mul_f32_e32 v93, 0xbfb8aa3b, v93
	v_mul_f32_e32 v94, 0xbfb8aa3b, v94
	v_mul_f32_e32 v95, 0xbfb8aa3b, v95
.Llru0_loop:
	ds_read_b128 v[172:175], v150
	ds_read_b128 v[178:181], v150 offset:64
	ds_read_b64 v[182:183], v151
	ds_read_b64 v[184:185], v151 offset:32
	ds_read_b64 v[186:187], v151 offset:64
	ds_read_b64 v[188:189], v151 offset:96
	s_add_u32 s64, s66, s0
	s_addc_u32 s65, s67, 0
	s_waitcnt lgkmcnt(4)
	v_mfma_f32_16x16x32_bf16 v[156:159], v[4:7], v[172:175], 0
	v_mfma_f32_16x16x32_bf16 v[96:99], v[0:3], v[172:175], 0
	v_mfma_f32_16x16x32_bf16 v[160:163], v[24:27], v[172:175], 0
	v_mfma_f32_16x16x32_bf16 v[100:103], v[32:35], v[172:175], 0
	v_mfma_f32_16x16x32_bf16 v[164:167], v[48:51], v[172:175], 0
	v_mfma_f32_16x16x32_bf16 v[104:107], v[56:59], v[172:175], 0
	v_mfma_f32_16x16x32_bf16 v[168:171], v[72:75], v[172:175], 0
	v_mfma_f32_16x16x32_bf16 v[108:111], v[80:83], v[172:175], 0
	v_mfma_f32_16x16x32_bf16 v[156:159], v[8:11], v[178:181], v[156:159]
	v_mfma_f32_16x16x32_bf16 v[96:99], v[12:15], v[178:181], v[96:99]
	v_mfma_f32_16x16x32_bf16 v[160:163], v[28:31], v[178:181], v[160:163]
	v_mfma_f32_16x16x32_bf16 v[100:103], v[36:39], v[178:181], v[100:103]
	v_mfma_f32_16x16x32_bf16 v[164:167], v[52:55], v[178:181], v[164:167]
	v_mfma_f32_16x16x32_bf16 v[104:107], v[60:63], v[178:181], v[104:107]
	v_mfma_f32_16x16x32_bf16 v[168:171], v[76:79], v[178:181], v[168:171]
	v_mfma_f32_16x16x32_bf16 v[108:111], v[84:87], v[178:181], v[108:111]
	s_waitcnt lgkmcnt(0)
; #define LAS __attribute__((address_space(3)))
; __device__ __forceinline__ float bf2f(bf16_t b) { return __uint_as_float(((unsigned)b) << 16); }
; __device__ __forceinline__ float sigmoidf_(float x) { return __builtin_amdgcn_rcpf(1.0f + __expf(-x)); }
; template <int DIR> __device__ __forceinline__ void lru_dir(const Params& p, int l, int n, int h, int lane, LAS bf16_t* XC, LAS float* STA, LAS float* STU) {
;     ...
;         for (int nf = 0; nf < 4; ++nf) {
;             const int jo = 16 * nf + 4 * q;
;             const bf16x4 xc4 = *(const LAS bf16x4*)(XC + (16 * mi + c) * 520 + 64 * h + jo);
;             const f32x4 zav = za[nf] + ba4[nf], zxv = zx[nf] + bx4[nf];
;             f32x4 av, uv;
; #pragma unroll
;             for (int r = 0; r < 4; ++r) {
;                 const float ra = sigmoidf_(zav[r]), ix = sigmoidf_(zxv[r]);
;                 const float la = ra * sp4[nf][r];
;                 av[r] = __expf(la);
;                 const float x2 = 2.0f * la;
;                 const float om = -x2 * (1.0f + x2 * (0.5f + x2 * (0.16666667f + x2 * (0.041666668f + x2 * (0.0083333338f + x2 * (0.0013888889f + x2 * 0.0001984127f))))));
;                 uv[r] = bf2f((bf16_t)xc4[r]) * ix * __builtin_amdgcn_sqrtf(fmaxf(om, 0.f));
;             }
;             *(LAS f32x4*)(STA + c * 68 + jo) = av; *(LAS f32x4*)(STU + c * 68 + jo) = uv;
	v_lshlrev_b32_e32 v204, 16, v182
	v_and_b32_e32 v205, 0xffff0000, v182
	v_lshlrev_b32_e32 v206, 16, v183
	v_and_b32_e32 v207, 0xffff0000, v183
	v_lshlrev_b32_e32 v208, 16, v184
	v_and_b32_e32 v209, 0xffff0000, v184
	v_lshlrev_b32_e32 v210, 16, v185
	v_and_b32_e32 v211, 0xffff0000, v185
	v_lshlrev_b32_e32 v212, 16, v186
	v_and_b32_e32 v213, 0xffff0000, v186
	v_lshlrev_b32_e32 v214, 16, v187
	v_and_b32_e32 v215, 0xffff0000, v187
	v_lshlrev_b32_e32 v216, 16, v188
	v_and_b32_e32 v217, 0xffff0000, v188
	v_lshlrev_b32_e32 v218, 16, v189
	v_and_b32_e32 v219, 0xffff0000, v189
	v_fmamk_f32 v192, v156, 0xbfb8aa3b, v16
	v_fmamk_f32 v195, v157, 0xbfb8aa3b, v17
	v_fmamk_f32 v198, v158, 0xbfb8aa3b, v18
	v_fmamk_f32 v201, v159, 0xbfb8aa3b, v19
	v_fmamk_f32 v193, v96, 0xbfb8aa3b, v20
	v_fmamk_f32 v196, v97, 0xbfb8aa3b, v21
	v_fmamk_f32 v199, v98, 0xbfb8aa3b, v22
	v_fmamk_f32 v202, v99, 0xbfb8aa3b, v23
	v_exp_f32_e32 v192, v192
	v_exp_f32_e32 v195, v195
	v_exp_f32_e32 v198, v198
	v_exp_f32_e32 v201, v201
	v_exp_f32_e32 v193, v193
	v_exp_f32_e32 v196, v196
	v_exp_f32_e32 v199, v199
	v_exp_f32_e32 v202, v202
	v_add_f32_e32 v192, 1.0, v192
	v_add_f32_e32 v195, 1.0, v195
	v_add_f32_e32 v198, 1.0, v198
	v_add_f32_e32 v201, 1.0, v201
	v_add_f32_e32 v193, 1.0, v193
	v_add_f32_e32 v196, 1.0, v196
	v_add_f32_e32 v199, 1.0, v199
	v_add_f32_e32 v202, 1.0, v202
	v_rcp_f32_e32 v192, v192
	v_rcp_f32_e32 v195, v195
	v_rcp_f32_e32 v198, v198
	v_rcp_f32_e32 v201, v201
	v_rcp_f32_e32 v193, v193
	v_rcp_f32_e32 v196, v196
	v_rcp_f32_e32 v199, v199
	v_rcp_f32_e32 v202, v202
	v_mul_f32_e32 v192, v148, v192
	v_mul_f32_e32 v195, v147, v195
	v_mul_f32_e32 v198, v146, v198
	v_mul_f32_e32 v201, v145, v201
	v_exp_f32_e32 v156, v192
	v_exp_f32_e32 v157, v195
	v_exp_f32_e32 v158, v198
	v_exp_f32_e32 v159, v201
	v_fma_f32 v192, -v156, v156, 1.0
	v_fma_f32 v195, -v157, v157, 1.0
	v_fma_f32 v198, -v158, v158, 1.0
	v_fma_f32 v201, -v159, v159, 1.0
	v_max_f32_e32 v192, 0, v192
	v_max_f32_e32 v195, 0, v195
	v_max_f32_e32 v198, 0, v198
	v_max_f32_e32 v201, 0, v201
	v_sqrt_f32_e32 v192, v192
	v_sqrt_f32_e32 v195, v195
	v_sqrt_f32_e32 v198, v198
	v_sqrt_f32_e32 v201, v201
	v_mul_f32_e32 v193, v193, v204
	v_mul_f32_e32 v196, v196, v205
	v_mul_f32_e32 v199, v199, v206
	v_mul_f32_e32 v202, v202, v207
	v_mul_f32_e32 v96, v193, v192
	v_mul_f32_e32 v97, v196, v195
	v_mul_f32_e32 v98, v199, v198
	v_mul_f32_e32 v99, v202, v201
	ds_write_b128 v154, v[156:159]
	ds_write_b128 v154, v[96:99] offset:4352
	v_fmamk_f32 v192, v160, 0xbfb8aa3b, v40
	v_fmamk_f32 v195, v161, 0xbfb8aa3b, v41
	v_fmamk_f32 v198, v162, 0xbfb8aa3b, v42
	v_fmamk_f32 v201, v163, 0xbfb8aa3b, v43
	v_fmamk_f32 v193, v100, 0xbfb8aa3b, v44
	v_fmamk_f32 v196, v101, 0xbfb8aa3b, v45
	v_fmamk_f32 v199, v102, 0xbfb8aa3b, v46
	v_fmamk_f32 v202, v103, 0xbfb8aa3b, v47
	v_exp_f32_e32 v192, v192
	v_exp_f32_e32 v195, v195
	v_exp_f32_e32 v198, v198
	v_exp_f32_e32 v201, v201
	v_exp_f32_e32 v193, v193
	v_exp_f32_e32 v196, v196
	v_exp_f32_e32 v199, v199
	v_exp_f32_e32 v202, v202
	v_add_f32_e32 v192, 1.0, v192
	v_add_f32_e32 v195, 1.0, v195
	v_add_f32_e32 v198, 1.0, v198
	v_add_f32_e32 v201, 1.0, v201
	v_add_f32_e32 v193, 1.0, v193
	v_add_f32_e32 v196, 1.0, v196
	v_add_f32_e32 v199, 1.0, v199
	v_add_f32_e32 v202, 1.0, v202
	v_rcp_f32_e32 v192, v192
	v_rcp_f32_e32 v195, v195
	v_rcp_f32_e32 v198, v198
	v_rcp_f32_e32 v201, v201
	v_rcp_f32_e32 v193, v193
	v_rcp_f32_e32 v196, v196
	v_rcp_f32_e32 v199, v199
	v_rcp_f32_e32 v202, v202
	v_mul_f32_e32 v192, v144, v192
	v_mul_f32_e32 v195, v143, v195
	v_mul_f32_e32 v198, v142, v198
	v_mul_f32_e32 v201, v141, v201
	v_exp_f32_e32 v160, v192
	v_exp_f32_e32 v161, v195
	v_exp_f32_e32 v162, v198
	v_exp_f32_e32 v163, v201
	v_fma_f32 v192, -v160, v160, 1.0
	v_fma_f32 v195, -v161, v161, 1.0
	v_fma_f32 v198, -v162, v162, 1.0
	v_fma_f32 v201, -v163, v163, 1.0
	v_max_f32_e32 v192, 0, v192
	v_max_f32_e32 v195, 0, v195
	v_max_f32_e32 v198, 0, v198
	v_max_f32_e32 v201, 0, v201
	v_sqrt_f32_e32 v192, v192
	v_sqrt_f32_e32 v195, v195
	v_sqrt_f32_e32 v198, v198
	v_sqrt_f32_e32 v201, v201
	v_mul_f32_e32 v193, v193, v208
	v_mul_f32_e32 v196, v196, v209
	v_mul_f32_e32 v199, v199, v210
	v_mul_f32_e32 v202, v202, v211
	v_mul_f32_e32 v100, v193, v192
	v_mul_f32_e32 v101, v196, v195
	v_mul_f32_e32 v102, v199, v198
	v_mul_f32_e32 v103, v202, v201
	ds_write_b128 v154, v[160:163] offset:64
	ds_write_b128 v154, v[100:103] offset:4416
	v_fmamk_f32 v192, v164, 0xbfb8aa3b, v64
	v_fmamk_f32 v195, v165, 0xbfb8aa3b, v65
	v_fmamk_f32 v198, v166, 0xbfb8aa3b, v66
	v_fmamk_f32 v201, v167, 0xbfb8aa3b, v67
	v_fmamk_f32 v193, v104, 0xbfb8aa3b, v68
	v_fmamk_f32 v196, v105, 0xbfb8aa3b, v69
	v_fmamk_f32 v199, v106, 0xbfb8aa3b, v70
	v_fmamk_f32 v202, v107, 0xbfb8aa3b, v71
	v_exp_f32_e32 v192, v192
	v_exp_f32_e32 v195, v195
	v_exp_f32_e32 v198, v198
	v_exp_f32_e32 v201, v201
	v_exp_f32_e32 v193, v193
	v_exp_f32_e32 v196, v196
	v_exp_f32_e32 v199, v199
	v_exp_f32_e32 v202, v202
	v_add_f32_e32 v192, 1.0, v192
	v_add_f32_e32 v195, 1.0, v195
	v_add_f32_e32 v198, 1.0, v198
	v_add_f32_e32 v201, 1.0, v201
	v_add_f32_e32 v193, 1.0, v193
	v_add_f32_e32 v196, 1.0, v196
	v_add_f32_e32 v199, 1.0, v199
	v_add_f32_e32 v202, 1.0, v202
	v_rcp_f32_e32 v192, v192
	v_rcp_f32_e32 v195, v195
	v_rcp_f32_e32 v198, v198
	v_rcp_f32_e32 v201, v201
	v_rcp_f32_e32 v193, v193
	v_rcp_f32_e32 v196, v196
	v_rcp_f32_e32 v199, v199
	v_rcp_f32_e32 v202, v202
	v_mul_f32_e32 v192, v140, v192
	v_mul_f32_e32 v195, v139, v195
	v_mul_f32_e32 v198, v138, v198
	v_mul_f32_e32 v201, v137, v201
	v_exp_f32_e32 v164, v192
	v_exp_f32_e32 v165, v195
	v_exp_f32_e32 v166, v198
	v_exp_f32_e32 v167, v201
; #define LAS __attribute__((address_space(3)))
; __device__ __forceinline__ float bf2f(bf16_t b) { return __uint_as_float(((unsigned)b) << 16); }
; __device__ __forceinline__ unsigned cvtpk(float lo, float hi) { const f32x2 v = (f32x2){lo, hi}; const bf16v2 b = __builtin_convertvector(v, bf16v2); return __builtin_bit_cast(unsigned, b); }
; __device__ __forceinline__ float sigmoidf_(float x) { return __builtin_amdgcn_rcpf(1.0f + __expf(-x)); }
; template <int DIR> __device__ __forceinline__ void lru_dir(const Params& p, int l, int n, int h, int lane, LAS bf16_t* XC, LAS float* STA, LAS float* STU) {
;     ...
;         for (int nf = 0; nf < 4; ++nf) {
;             const int jo = 16 * nf + 4 * q;
;             const bf16x4 xc4 = *(const LAS bf16x4*)(XC + (16 * mi + c) * 520 + 64 * h + jo);
;             const f32x4 zav = za[nf] + ba4[nf], zxv = zx[nf] + bx4[nf];
;             f32x4 av, uv;
; #pragma unroll
;             for (int r = 0; r < 4; ++r) {
;                 const float ra = sigmoidf_(zav[r]), ix = sigmoidf_(zxv[r]);
;                 const float la = ra * sp4[nf][r];
;                 av[r] = __expf(la);
;                 const float x2 = 2.0f * la;
;                 const float om = -x2 * (1.0f + x2 * (0.5f + x2 * (0.16666667f + x2 * (0.041666668f + x2 * (0.0083333338f + x2 * (0.0013888889f + x2 * 0.0001984127f))))));
;                 uv[r] = bf2f((bf16_t)xc4[r]) * ix * __builtin_amdgcn_sqrtf(fmaxf(om, 0.f));
;             }
;             *(LAS f32x4*)(STA + c * 68 + jo) = av; *(LAS f32x4*)(STU + c * 68 + jo) = uv;
;         }
;         LDS_FENCE();
;         float aa[16], uu[16];
; #pragma unroll
;         for (int s = 0; s < 16; ++s) { aa[s] = STA[s * 68 + j]; uu[s] = STU[s * 68 + j]; }
;         LDS_FENCE();
; #pragma unroll
;         for (int s = 0; s < 16; ++s) {
;             const int tl = DIR == 0 ? s : 15 - s;
;             hcar = aa[tl] * hcar + uu[tl]; P *= aa[tl];
;             const size_t row = (size_t)(t0 + 16 * mi + tl);
;             if (DIR == 0) { const unsigned w = cvtpk(hcar, P); y[row * D + 64 * h + j] = (bf16_t)(w & 0xffffu); y[row * D + 512 + 64 * h + j] = (bf16_t)(w >> 16); }
;             else { const unsigned w = cvtpk(bf2f(hfp[tl]) + hcar, P); y[row * D + 64 * h + j] = (bf16_t)(w & 0xffffu); __builtin_nontemporal_store((bf16_t)(w >> 16), PB + row * 512 + 64 * h + j); }
;         }
	v_fma_f32 v192, -v164, v164, 1.0
	v_fma_f32 v195, -v165, v165, 1.0
	v_fma_f32 v198, -v166, v166, 1.0
	v_fma_f32 v201, -v167, v167, 1.0
	v_max_f32_e32 v192, 0, v192
	v_max_f32_e32 v195, 0, v195
	v_max_f32_e32 v198, 0, v198
	v_max_f32_e32 v201, 0, v201
	v_sqrt_f32_e32 v192, v192
	v_sqrt_f32_e32 v195, v195
	v_sqrt_f32_e32 v198, v198
	v_sqrt_f32_e32 v201, v201
	v_mul_f32_e32 v193, v193, v212
	v_mul_f32_e32 v196, v196, v213
	v_mul_f32_e32 v199, v199, v214
	v_mul_f32_e32 v202, v202, v215
	v_mul_f32_e32 v104, v193, v192
	v_mul_f32_e32 v105, v196, v195
	v_mul_f32_e32 v106, v199, v198
	v_mul_f32_e32 v107, v202, v201
	ds_write_b128 v154, v[164:167] offset:128
	ds_write_b128 v154, v[104:107] offset:4480
	v_fmamk_f32 v192, v168, 0xbfb8aa3b, v88
	v_fmamk_f32 v195, v169, 0xbfb8aa3b, v89
	v_fmamk_f32 v198, v170, 0xbfb8aa3b, v90
	v_fmamk_f32 v201, v171, 0xbfb8aa3b, v91
	v_fmamk_f32 v193, v108, 0xbfb8aa3b, v92
	v_fmamk_f32 v196, v109, 0xbfb8aa3b, v93
	v_fmamk_f32 v199, v110, 0xbfb8aa3b, v94
	v_fmamk_f32 v202, v111, 0xbfb8aa3b, v95
	v_exp_f32_e32 v192, v192
	v_exp_f32_e32 v195, v195
	v_exp_f32_e32 v198, v198
	v_exp_f32_e32 v201, v201
	v_exp_f32_e32 v193, v193
	v_exp_f32_e32 v196, v196
	v_exp_f32_e32 v199, v199
	v_exp_f32_e32 v202, v202
	v_add_f32_e32 v192, 1.0, v192
	v_add_f32_e32 v195, 1.0, v195
	v_add_f32_e32 v198, 1.0, v198
	v_add_f32_e32 v201, 1.0, v201
	v_add_f32_e32 v193, 1.0, v193
	v_add_f32_e32 v196, 1.0, v196
	v_add_f32_e32 v199, 1.0, v199
	v_add_f32_e32 v202, 1.0, v202
	v_rcp_f32_e32 v192, v192
	v_rcp_f32_e32 v195, v195
	v_rcp_f32_e32 v198, v198
	v_rcp_f32_e32 v201, v201
	v_rcp_f32_e32 v193, v193
	v_rcp_f32_e32 v196, v196
	v_rcp_f32_e32 v199, v199
	v_rcp_f32_e32 v202, v202
	v_mul_f32_e32 v192, v136, v192
	v_mul_f32_e32 v195, v135, v195
	v_mul_f32_e32 v198, v134, v198
	v_mul_f32_e32 v201, v149, v201
	v_exp_f32_e32 v168, v192
	v_exp_f32_e32 v169, v195
	v_exp_f32_e32 v170, v198
	v_exp_f32_e32 v171, v201
	v_fma_f32 v192, -v168, v168, 1.0
	v_fma_f32 v195, -v169, v169, 1.0
	v_fma_f32 v198, -v170, v170, 1.0
	v_fma_f32 v201, -v171, v171, 1.0
	v_max_f32_e32 v192, 0, v192
	v_max_f32_e32 v195, 0, v195
	v_max_f32_e32 v198, 0, v198
	v_max_f32_e32 v201, 0, v201
	v_sqrt_f32_e32 v192, v192
	v_sqrt_f32_e32 v195, v195
	v_sqrt_f32_e32 v198, v198
	v_sqrt_f32_e32 v201, v201
	v_mul_f32_e32 v193, v193, v216
	v_mul_f32_e32 v196, v196, v217
	v_mul_f32_e32 v199, v199, v218
	v_mul_f32_e32 v202, v202, v219
	v_mul_f32_e32 v108, v193, v192
	v_mul_f32_e32 v109, v196, v195
	v_mul_f32_e32 v110, v199, v198
	v_mul_f32_e32 v111, v202, v201
	ds_write_b128 v154, v[168:171] offset:192
	ds_write_b128 v154, v[108:111] offset:4544
	s_waitcnt lgkmcnt(0)
	ds_read_b32 v204, v155
	ds_read_b32 v172, v155 offset:4352
	ds_read_b32 v205, v155 offset:272
	ds_read_b32 v173, v155 offset:4624
	ds_read_b32 v206, v155 offset:544
	ds_read_b32 v174, v155 offset:4896
	ds_read_b32 v207, v155 offset:816
	ds_read_b32 v175, v155 offset:5168
	ds_read_b32 v208, v155 offset:1088
	ds_read_b32 v178, v155 offset:5440
	ds_read_b32 v209, v155 offset:1360
	ds_read_b32 v179, v155 offset:5712
	ds_read_b32 v210, v155 offset:1632
	ds_read_b32 v180, v155 offset:5984
	ds_read_b32 v211, v155 offset:1904
	ds_read_b32 v181, v155 offset:6256
	s_waitcnt lgkmcnt(14)
	v_fma_f32 v130, v130, v204, v172
	v_mul_f32_e32 v129, v129, v204
	v_cvt_pk_bf16_f32 v190, v130, v129
	global_store_short v220, v190, s[64:65] offset:-4096
	global_store_short_d16_hi v220, v190, s[64:65] offset:-3072
	ds_read_b32 v212, v155 offset:2176
	ds_read_b32 v182, v155 offset:6528
	s_waitcnt lgkmcnt(14)
	v_fma_f32 v130, v130, v205, v173
	v_mul_f32_e32 v129, v129, v205
	v_cvt_pk_bf16_f32 v191, v130, v129
	global_store_short v220, v191, s[64:65] offset:-2048
	global_store_short_d16_hi v220, v191, s[64:65] offset:-1024
	ds_read_b32 v213, v155 offset:2448
	ds_read_b32 v183, v155 offset:6800
	s_waitcnt lgkmcnt(14)
	v_fma_f32 v130, v130, v206, v174
	v_mul_f32_e32 v129, v129, v206
	v_cvt_pk_bf16_f32 v190, v130, v129
	global_store_short v220, v190, s[64:65] offset:0
	global_store_short_d16_hi v220, v190, s[64:65] offset:1024
	ds_read_b32 v214, v155 offset:2720
	ds_read_b32 v184, v155 offset:7072
	s_waitcnt lgkmcnt(14)
	v_fma_f32 v130, v130, v207, v175
	v_mul_f32_e32 v129, v129, v207
	v_cvt_pk_bf16_f32 v191, v130, v129
	global_store_short v220, v191, s[64:65] offset:2048
	global_store_short_d16_hi v220, v191, s[64:65] offset:3072
	ds_read_b32 v215, v155 offset:2992
	ds_read_b32 v185, v155 offset:7344
	s_waitcnt lgkmcnt(14)
	v_fma_f32 v130, v130, v208, v178
	v_mul_f32_e32 v129, v129, v208
	v_cvt_pk_bf16_f32 v190, v130, v129
	s_add_u32 s64, s64, 0x2000
	s_addc_u32 s65, s65, 0
	global_store_short v220, v190, s[64:65] offset:-4096
	global_store_short_d16_hi v220, v190, s[64:65] offset:-3072
	ds_read_b32 v216, v155 offset:3264
	ds_read_b32 v186, v155 offset:7616
	s_waitcnt lgkmcnt(14)
	v_fma_f32 v130, v130, v209, v179
	v_mul_f32_e32 v129, v129, v209
	v_cvt_pk_bf16_f32 v191, v130, v129
	global_store_short v220, v191, s[64:65] offset:-2048
	global_store_short_d16_hi v220, v191, s[64:65] offset:-1024
	ds_read_b32 v217, v155 offset:3536
	ds_read_b32 v187, v155 offset:7888
	s_waitcnt lgkmcnt(14)
	v_fma_f32 v130, v130, v210, v180
	v_mul_f32_e32 v129, v129, v210
	v_cvt_pk_bf16_f32 v190, v130, v129
	global_store_short v220, v190, s[64:65] offset:0
	global_store_short_d16_hi v220, v190, s[64:65] offset:1024
	ds_read_b32 v218, v155 offset:3808
	ds_read_b32 v188, v155 offset:8160
	s_waitcnt lgkmcnt(14)
; __device__ __forceinline__ float bf2f(bf16_t b) { return __uint_as_float(((unsigned)b) << 16); }
; __device__ __forceinline__ unsigned cvtpk(float lo, float hi) { const f32x2 v = (f32x2){lo, hi}; const bf16v2 b = __builtin_convertvector(v, bf16v2); return __builtin_bit_cast(unsigned, b); }
; template <int DIR> __device__ __forceinline__ void lru_dir(const Params& p, int l, int n, int h, int lane, LAS bf16_t* XC, LAS float* STA, LAS float* STU) {
;     ...
;     const float* lam = p.in[10] + (size_t)(l * 2 + DIR) * 512 + 64 * h; const float* b_a = p.in[7] + (size_t)(l * 2 + DIR) * 512 + 64 * h; const float* b_x = p.in[9] + (size_t)(l * 2 + DIR) * 512 + 64 * h;
;     const bf16_t* LWa = LW + ((size_t)(DIR * 2 + 0) * 8 + h) * 4096 + c * 64 + 8 * q; const bf16_t* LWx = LW + ((size_t)(DIR * 2 + 1) * 8 + h) * 4096 + c * 64 + 8 * q;
;     bf16x8 wa[4][2], wx[4][2]; f32x4 sp4[4], ba4[4], bx4[4];
; #pragma unroll
;     for (int nf = 0; nf < 4; ++nf) {
; #pragma unroll
;         for (int ks = 0; ks < 2; ++ks) { wa[nf][ks] = *(const bf16x8*)(LWa + nf * 1024 + 32 * ks); wx[nf][ks] = *(const bf16x8*)(LWx + nf * 1024 + 32 * ks); }
;         const f32x4 lam4 = *(const f32x4*)(lam + 16 * nf + 4 * q); ba4[nf] = *(const f32x4*)(b_a + 16 * nf + 4 * q); bx4[nf] = *(const f32x4*)(b_x + 16 * nf + 4 * q);
; #pragma unroll
;         for (int r = 0; r < 4; ++r) { const float e = __expf(-lam4[r]); const float l1p = e < 0.05f ? e * (1.0f - e * (0.5f - e * (0.33333334f - e * 0.25f))) : __logf(1.0f + e); sp4[nf][r] = -8.0f * l1p; }
;     ...
; #pragma unroll
;         for (int s = 0; s < 16; ++s) {
;             const int tl = DIR == 0 ? s : 15 - s;
;             hcar = aa[tl] * hcar + uu[tl]; P *= aa[tl];
;             const size_t row = (size_t)(t0 + 16 * mi + tl);
;             if (DIR == 0) { const unsigned w = cvtpk(hcar, P); y[row * D + 64 * h + j] = (bf16_t)(w & 0xffffu); y[row * D + 512 + 64 * h + j] = (bf16_t)(w >> 16); }
;             else { const unsigned w = cvtpk(bf2f(hfp[tl]) + hcar, P); y[row * D + 64 * h + j] = (bf16_t)(w & 0xffffu); __builtin_nontemporal_store((bf16_t)(w >> 16), PB + row * 512 + 64 * h + j); }
;         }
;     }
;     Aprod[(size_t)(DIR * NCH + n) * 512 + 64 * h + j] = P; Hend[(size_t)(DIR * NCH + n) * 512 + 64 * h + j] = hcar;
	v_fma_f32 v130, v130, v211, v181
	v_mul_f32_e32 v129, v129, v211
	v_cvt_pk_bf16_f32 v191, v130, v129
	global_store_short v220, v191, s[64:65] offset:2048
	global_store_short_d16_hi v220, v191, s[64:65] offset:3072
	ds_read_b32 v219, v155 offset:4080
	ds_read_b32 v189, v155 offset:8432
	s_waitcnt lgkmcnt(14)
	v_fma_f32 v130, v130, v212, v182
	v_mul_f32_e32 v129, v129, v212
	v_cvt_pk_bf16_f32 v190, v130, v129
	s_add_u32 s64, s64, 0x2000
	s_addc_u32 s65, s65, 0
	global_store_short v220, v190, s[64:65] offset:-4096
	global_store_short_d16_hi v220, v190, s[64:65] offset:-3072
	s_waitcnt lgkmcnt(12)
	v_fma_f32 v130, v130, v213, v183
	v_mul_f32_e32 v129, v129, v213
	v_cvt_pk_bf16_f32 v191, v130, v129
	global_store_short v220, v191, s[64:65] offset:-2048
	global_store_short_d16_hi v220, v191, s[64:65] offset:-1024
	s_waitcnt lgkmcnt(10)
	v_fma_f32 v130, v130, v214, v184
	v_mul_f32_e32 v129, v129, v214
	v_cvt_pk_bf16_f32 v190, v130, v129
	global_store_short v220, v190, s[64:65] offset:0
	global_store_short_d16_hi v220, v190, s[64:65] offset:1024
	s_waitcnt lgkmcnt(8)
	v_fma_f32 v130, v130, v215, v185
	v_mul_f32_e32 v129, v129, v215
	v_cvt_pk_bf16_f32 v191, v130, v129
	global_store_short v220, v191, s[64:65] offset:2048
	global_store_short_d16_hi v220, v191, s[64:65] offset:3072
	s_waitcnt lgkmcnt(6)
	v_fma_f32 v130, v130, v216, v186
	v_mul_f32_e32 v129, v129, v216
	v_cvt_pk_bf16_f32 v190, v130, v129
	s_add_u32 s64, s64, 0x2000
	s_addc_u32 s65, s65, 0
	global_store_short v220, v190, s[64:65] offset:-4096
	global_store_short_d16_hi v220, v190, s[64:65] offset:-3072
	s_waitcnt lgkmcnt(4)
	v_fma_f32 v130, v130, v217, v187
	v_mul_f32_e32 v129, v129, v217
	v_cvt_pk_bf16_f32 v191, v130, v129
	global_store_short v220, v191, s[64:65] offset:-2048
	global_store_short_d16_hi v220, v191, s[64:65] offset:-1024
	s_waitcnt lgkmcnt(2)
	v_fma_f32 v130, v130, v218, v188
	v_mul_f32_e32 v129, v129, v218
	v_cvt_pk_bf16_f32 v190, v130, v129
	global_store_short v220, v190, s[64:65] offset:0
	global_store_short_d16_hi v220, v190, s[64:65] offset:1024
	s_waitcnt lgkmcnt(0)
	v_fma_f32 v130, v130, v219, v189
	v_mul_f32_e32 v129, v129, v219
	v_cvt_pk_bf16_f32 v191, v130, v129
	global_store_short v220, v191, s[64:65] offset:2048
	global_store_short_d16_hi v220, v191, s[64:65] offset:3072
	s_add_u32 s0, s0, 0x8000
	s_addc_u32 s1, s1, 0
	v_add_u32_e32 v150, 0x4100, v150
	v_add_u32_e32 v151, 0x4100, v151
	s_cmp_lg_u32 s0, 0x20000
	s_cbranch_scc1 .Llru0_loop
	v_add_u32_e32 v156, 0x1000, v155
	v_add_u32_e32 v157, 0x1200, v155
	v_add_u32_e32 v158, 0x400, v155
	v_add_u32_e32 v159, 0x1400, v155
	v_add_u32_e32 v160, 0x1600, v155
	v_add_u32_e32 v161, 0x800, v155
	v_add_u32_e32 v162, 0x1800, v155
	v_add_u32_e32 v163, 0x1a00, v155
	v_add_u32_e32 v164, 0xc00, v155
	v_add_u32_e32 v165, 0x1c00, v155
	v_add_u32_e32 v166, 0x1e00, v155
	s_ashr_i32 s5, s4, 31
	s_lshl_b64 s[0:1], s[4:5], 9
	v_lshl_add_u64 v[0:1], s[0:1], 0, v[124:125]
	v_or_b32_e32 v0, v0, v126
	v_readlane_b32 s0, v254, 11
	v_lshlrev_b64 v[0:1], 2, v[0:1]
	v_readlane_b32 s1, v254, 12
	v_lshlrev_b32_e32 v6, 1, v121
	v_mov_b32_e32 v7, v177
	v_lshl_add_u64 v[2:3], s[0:1], 0, v[0:1]
	v_readlane_b32 s0, v254, 13
	v_readlane_b32 s1, v254, 14
	v_lshlrev_b32_e32 v8, 1, v133
	v_mov_b32_e32 v9, v177
	v_lshl_add_u64 v[6:7], v[114:115], 0, v[6:7]
	v_lshl_add_u64 v[0:1], s[0:1], 0, v[0:1]
	v_lshl_add_u64 v[6:7], v[6:7], 0, v[8:9]
	s_mov_b64 s[0:1], 0x20000
	v_lshl_add_u64 v[80:81], v[6:7], 0, s[0:1]
	s_mov_b64 s[0:1], 0x30000
	global_store_dword v[0:1], v130, off
	v_lshl_add_u64 v[0:1], s[22:23], 0, v[112:113]
	v_lshl_add_u64 v[78:79], v[6:7], 0, s[0:1]
	v_mov_b32_e32 v121, v177
	s_mov_b32 s0, 0x20000
	v_lshl_add_u64 v[76:77], v[0:1], 0, v[120:121]
	v_add_co_u32_e32 v0, vcc, s0, v6
	v_lshl_add_u64 v[4:5], s[38:39], 0, v[112:113]
	s_nop 0
	v_addc_co_u32_e32 v1, vcc, 0, v7, vcc
	v_lshl_add_u64 v[92:93], v[4:5], 0, v[120:121]
	v_add_co_u32_e32 v4, vcc, 0x30000, v6
	global_store_dword v[2:3], v129, off
	v_lshl_add_u64 v[2:3], s[26:27], 0, v[112:113]
	v_addc_co_u32_e32 v5, vcc, 0, v7, vcc
	v_lshl_add_u64 v[88:89], v[2:3], 0, v[120:121]
	global_load_dwordx4 v[192:195], v[76:77], off
	global_load_dwordx4 v[196:199], v[76:77], off offset:64
	global_load_dwordx4 v[200:203], v[76:77], off offset:128
	global_load_dwordx4 v[204:207], v[76:77], off offset:192
	s_nop 0
	global_load_dwordx4 v[0:3], v[0:1], off
	s_nop 0
	global_load_dwordx4 v[4:7], v[4:5], off
	s_nop 0
	global_load_dwordx4 v[8:11], v[80:81], off offset:64
	global_load_dwordx4 v[12:15], v[78:79], off offset:64
	global_load_dwordx4 v[16:19], v[88:89], off
	global_load_dwordx4 v[20:23], v[92:93], off
	s_waitcnt vmcnt(6)
	v_mul_f32_e32 v24, 0xbfb8aa3b, v192
	v_exp_f32_e32 v24, v24
	s_nop 0
	v_cmp_ngt_f32_e32 vcc, s6, v24
	s_and_saveexec_b64 s[0:1], vcc
	s_xor_b64 s[30:31], exec, s[0:1]
	s_cbranch_execz .LBB0_260
	v_add_f32_e32 v24, 1.0, v24
	v_cmp_gt_f32_e32 vcc, s25, v24
	s_nop 1
	v_cndmask_b32_e64 v28, 0, 32, vcc
	v_ldexp_f32 v24, v24, v28
	v_log_f32_e32 v24, v24
	s_nop 0
	v_mul_f32_e32 v28, 0x3f317217, v24
	v_fma_f32 v28, v24, s36, -v28
	v_fmac_f32_e32 v28, 0x3377d1cf, v24
	v_fmac_f32_e32 v28, 0x3f317217, v24
	v_cmp_lt_f32_e64 s[0:1], |v24|, s37
	s_nop 1
	v_cndmask_b32_e64 v24, v24, v28, s[0:1]
	v_cndmask_b32_e32 v28, 0, v232, vcc
	v_sub_f32_e32 v100, v24, v28

; #define LAS __attribute__((address_space(3)))
; __device__ __forceinline__ float bf2f(bf16_t b) { return __uint_as_float(((unsigned)b) << 16); }
; __device__ __forceinline__ float sigmoidf_(float x) { return __builtin_amdgcn_rcpf(1.0f + __expf(-x)); }
; template <int DIR> __device__ __forceinline__ void lru_dir(const Params& p, int l, int n, int h, int lane, LAS bf16_t* XC, LAS float* STA, LAS float* STU) {
;     ...
;         for (int r = 0; r < 4; ++r) { const float e = __expf(-lam4[r]); const float l1p = e < 0.05f ? e * (1.0f - e * (0.5f - e * (0.33333334f - e * 0.25f))) : __logf(1.0f + e); sp4[nf][r] = -8.0f * l1p; }
;     }
;     float hcar = 0.f, P = 1.f;
; #pragma unroll 1
;     for (int g = 0; g < 4; ++g) {
;         const int mi = DIR == 0 ? g : 3 - g;
;         bf16_t hfp[16];
;         if (DIR == 1) {
; #pragma unroll
;             for (int s = 0; s < 16; ++s) hfp[s] = y[(size_t)(t0 + 16 * mi + s) * D + 64 * h + j];
;         }
;         bf16x8 xf[2];
; #pragma unroll
;         for (int ks = 0; ks < 2; ++ks) xf[ks] = *(const LAS bf16x8*)(XC + (16 * mi + c) * 520 + 64 * h + 32 * ks + 8 * q);
;         f32x4 za[4], zx[4];
; #pragma unroll
;         for (int nf = 0; nf < 4; ++nf) { za[nf] = (f32x4){0.f, 0.f, 0.f, 0.f}; zx[nf] = za[nf];
;             za[nf] = mfma16(wa[nf][0], xf[0], za[nf]); za[nf] = mfma16(wa[nf][1], xf[1], za[nf]);
;             zx[nf] = mfma16(wx[nf][0], xf[0], zx[nf]); zx[nf] = mfma16(wx[nf][1], xf[1], zx[nf]); }
; #pragma unroll
;         for (int nf = 0; nf < 4; ++nf) {
;             const int jo = 16 * nf + 4 * q;
;             const bf16x4 xc4 = *(const LAS bf16x4*)(XC + (16 * mi + c) * 520 + 64 * h + jo);
;             const f32x4 zav = za[nf] + ba4[nf], zxv = zx[nf] + bx4[nf];
;             f32x4 av, uv;
; #pragma unroll
;             for (int r = 0; r < 4; ++r) {
;                 const float ra = sigmoidf_(zav[r]), ix = sigmoidf_(zxv[r]);
;                 const float la = ra * sp4[nf][r];
;                 av[r] = __expf(la);
;                 const float x2 = 2.0f * la;
;                 const float om = -x2 * (1.0f + x2 * (0.5f + x2 * (0.16666667f + x2 * (0.041666668f + x2 * (0.0083333338f + x2 * (0.0013888889f + x2 * 0.0001984127f))))));
;                 uv[r] = bf2f((bf16_t)xc4[r]) * ix * __builtin_amdgcn_sqrtf(fmaxf(om, 0.f));
.LBB0_320:
	s_andn2_saveexec_b64 s[0:1], s[30:31]
	v_fmamk_f32 v99, v112, 0xbe800000, v226
	v_fma_f32 v99, -v112, v99, 0.5
	v_fma_f32 v99, -v112, v99, 1.0
	v_mul_f32_e32 v99, v112, v99
	s_or_b64 exec, exec, s[0:1]
	s_lshl_b64 s[0:1], s[28:29], 10
	s_add_u32 s0, s56, s0
	v_mul_f32_e32 v169, 0xc138aa3b, v96
	v_lshl_add_u32 v96, v124, 1, 0
	s_addc_u32 s1, s57, s1
	v_mul_f32_e32 v167, 0xc138aa3b, v98
	v_mul_f32_e32 v168, 0xc138aa3b, v97
	v_mul_f32_e32 v170, 0xc138aa3b, v111
	v_mul_f32_e32 v171, 0xc138aa3b, v110
	v_mul_f32_e32 v172, 0xc138aa3b, v109
	v_mul_f32_e32 v173, 0xc138aa3b, v108
	v_mul_f32_e32 v174, 0xc138aa3b, v107
	v_mul_f32_e32 v175, 0xc138aa3b, v106
	v_mul_f32_e32 v182, 0xc138aa3b, v105
	v_mul_f32_e32 v183, 0xc138aa3b, v104
	v_mul_f32_e32 v184, 0xc138aa3b, v103
	v_mul_f32_e32 v185, 0xc138aa3b, v102
	v_mul_f32_e32 v186, 0xc138aa3b, v101
	v_mul_f32_e32 v187, 0xc138aa3b, v100
	v_lshl_add_u32 v188, v133, 1, v96
	v_mul_f32_e32 v190, 0xc138aa3b, v99
	v_lshl_add_u32 v191, v132, 1, v96
	v_lshl_add_u64 v[128:129], s[0:1], 0, v[118:119]
	v_lshl_add_u64 v[130:131], s[56:57], 0, v[116:117]
	v_mov_b32_e32 v135, 1.0
	v_mov_b32_e32 v132, 0
	s_mov_b32 s0, 48
.LBB0_323:
	v_add_u32_e32 v133, s0, v127
	v_mad_u32_u24 v100, v133, s7, v188
	ds_read_b128 v[96:99], v100
	ds_read_b128 v[120:123], v100 offset:64
	v_mad_u32_u24 v133, v133, s7, v191
	ds_read_b64 v[146:147], v133
	v_lshl_add_u64 v[136:137], v[130:131], 0, v[176:177]
	s_waitcnt lgkmcnt(2)
	v_mfma_f32_16x16x32_bf16 v[100:103], v[0:3], v[96:99], 0
	s_mov_b32 s1, 0x1877000
	v_add_co_u32_e32 v150, vcc, s1, v136
	s_waitcnt lgkmcnt(1)
	v_mfma_f32_16x16x32_bf16 v[138:141], v[8:11], v[120:123], v[100:103]
	s_waitcnt lgkmcnt(0)
	v_and_b32_e32 v149, 0xffff0000, v147
	v_lshlrev_b32_e32 v148, 16, v147
	v_addc_co_u32_e32 v151, vcc, 0, v137, vcc
	v_mfma_f32_16x16x32_bf16 v[100:103], v[4:7], v[96:99], 0
	s_mov_b32 s1, 0x1876000
	v_and_b32_e32 v147, 0xffff0000, v146
	v_lshlrev_b32_e32 v146, 16, v146
	v_mfma_f32_16x16x32_bf16 v[142:145], v[12:15], v[120:123], v[100:103]
	global_load_ushort v189, v[150:151], off offset:2048
	global_load_ushort v204, v[150:151], off
	s_movk_i32 s28, 0xc000
	s_mov_b32 s29, -1
	v_mfma_f32_16x16x32_bf16 v[100:103], v[24:27], v[96:99], 0
	s_add_i32 s0, s0, -16
	s_cmp_lg_u32 s0, -16
	v_mfma_f32_16x16x32_bf16 v[116:119], v[28:31], v[120:123], v[100:103]
	v_mfma_f32_16x16x32_bf16 v[100:103], v[32:35], v[96:99], 0
	v_mfma_f32_16x16x32_bf16 v[112:115], v[36:39], v[120:123], v[100:103]
	s_nop 5
	v_add_f32_e32 v116, v40, v116
	v_mul_f32_e32 v116, 0xbfb8aa3b, v116
	v_exp_f32_e32 v116, v116
	v_mfma_f32_16x16x32_bf16 v[100:103], v[48:51], v[96:99], 0
	v_add_f32_e32 v117, v41, v117
	v_add_f32_e32 v112, v44, v112
	v_add_f32_e32 v116, 1.0, v116
	v_mfma_f32_16x16x32_bf16 v[108:111], v[52:55], v[120:123], v[100:103]
	v_mul_f32_e32 v112, 0xbfb8aa3b, v112
	v_exp_f32_e32 v112, v112
	v_mul_f32_e32 v117, 0xbfb8aa3b, v117
	v_mfma_f32_16x16x32_bf16 v[100:103], v[56:59], v[96:99], 0
	v_exp_f32_e32 v117, v117
	v_add_f32_e32 v112, 1.0, v112
	v_add_f32_e32 v113, v45, v113
	v_mfma_f32_16x16x32_bf16 v[104:107], v[60:63], v[120:123], v[100:103]
	v_add_f32_e32 v117, 1.0, v117
	v_mul_f32_e32 v113, 0xbfb8aa3b, v113
	v_exp_f32_e32 v113, v113
	s_waitcnt vmcnt(7)
	v_mfma_f32_16x16x32_bf16 v[100:103], v[72:75], v[96:99], 0
	v_add_f32_e32 v118, v42, v118
	v_mul_f32_e32 v118, 0xbfb8aa3b, v118
	v_add_f32_e32 v113, 1.0, v113
	s_waitcnt vmcnt(5)
	v_mfma_f32_16x16x32_bf16 v[96:99], v[80:83], v[96:99], 0
	v_exp_f32_e32 v118, v118
	v_add_f32_e32 v114, v46, v114
	v_mul_f32_e32 v114, 0xbfb8aa3b, v114
	v_mfma_f32_16x16x32_bf16 v[100:103], v[76:79], v[120:123], v[100:103]
	v_add_f32_e32 v118, 1.0, v118
	v_exp_f32_e32 v114, v114
	v_add_f32_e32 v119, v43, v119
	s_waitcnt vmcnt(4)
	v_mfma_f32_16x16x32_bf16 v[96:99], v[84:87], v[120:123], v[96:99]
	v_add_f32_e32 v120, v16, v138
	v_mul_f32_e32 v120, 0xbfb8aa3b, v120
	v_exp_f32_e32 v120, v120
	v_add_f32_e32 v121, v20, v142
	v_mul_f32_e32 v121, 0xbfb8aa3b, v121
	v_exp_f32_e32 v121, v121
	v_add_f32_e32 v120, 1.0, v120
	v_rcp_f32_e32 v120, v120
	v_add_f32_e32 v114, 1.0, v114
	v_add_f32_e32 v121, 1.0, v121
	v_rcp_f32_e32 v138, v121
	v_mul_f32_e32 v121, v187, v120
	v_exp_f32_e32 v120, v121
	s_nop 0
	v_fma_f32 v121, -v120, v120, 1.0
	v_max_f32_e32 v121, 0, v121
	v_sqrt_f32_e32 v142, v121
	v_add_f32_e32 v121, v17, v139
	v_mul_f32_e32 v121, 0xbfb8aa3b, v121
	v_exp_f32_e32 v121, v121
	v_add_f32_e32 v122, v21, v143
	v_mul_f32_e32 v122, 0xbfb8aa3b, v122
	v_exp_f32_e32 v122, v122
	v_add_f32_e32 v121, 1.0, v121
	v_rcp_f32_e32 v121, v121
	v_add_f32_e32 v122, 1.0, v122
	v_rcp_f32_e32 v139, v122
	v_mul_f32_e32 v122, v186, v121
	v_exp_f32_e32 v121, v122
	s_nop 0
	v_fma_f32 v122, -v121, v121, 1.0
	v_max_f32_e32 v122, 0, v122
	v_sqrt_f32_e32 v143, v122
	v_add_f32_e32 v122, v18, v140
	v_mul_f32_e32 v122, 0xbfb8aa3b, v122
	v_exp_f32_e32 v122, v122
	v_add_f32_e32 v123, v22, v144
	v_mul_f32_e32 v123, 0xbfb8aa3b, v123
	v_exp_f32_e32 v123, v123
	v_add_f32_e32 v122, 1.0, v122
	v_rcp_f32_e32 v122, v122
	v_pk_mul_f32 v[138:139], v[138:139], v[146:147]
	v_add_f32_e32 v123, 1.0, v123
	v_rcp_f32_e32 v140, v123
	v_mul_f32_e32 v123, v185, v122
	v_exp_f32_e32 v122, v123
	s_nop 0
	v_fma_f32 v123, -v122, v122, 1.0
	v_max_f32_e32 v123, 0, v123
	v_sqrt_f32_e32 v144, v123
	v_add_f32_e32 v123, v19, v141
	v_mul_f32_e32 v123, 0xbfb8aa3b, v123
	v_exp_f32_e32 v123, v123
	v_add_f32_e32 v134, v23, v145
	v_mul_f32_e32 v134, 0xbfb8aa3b, v134
	v_exp_f32_e32 v134, v134
	v_add_f32_e32 v123, 1.0, v123
	v_rcp_f32_e32 v123, v123
	v_pk_mul_f32 v[206:207], v[138:139], v[142:143]
	v_add_f32_e32 v134, 1.0, v134
	v_rcp_f32_e32 v141, v134
; #define LAS __attribute__((address_space(3)))
; __device__ __forceinline__ float bf2f(bf16_t b) { return __uint_as_float(((unsigned)b) << 16); }
; __device__ __forceinline__ float sigmoidf_(float x) { return __builtin_amdgcn_rcpf(1.0f + __expf(-x)); }
; __device__ __forceinline__ f32x4 mfma16(bf16x8 a, bf16x8 b, f32x4 c) { return __builtin_amdgcn_mfma_f32_16x16x32_bf16(a, b, c, 0, 0, 0); }
; template <int DIR> __device__ __forceinline__ void lru_dir(const Params& p, int l, int n, int h, int lane, LAS bf16_t* XC, LAS float* STA, LAS float* STU) {
;     ...
;             for (int s = 0; s < 16; ++s) hfp[s] = y[(size_t)(t0 + 16 * mi + s) * D + 64 * h + j];
;         }
;         bf16x8 xf[2];
; #pragma unroll
;         for (int ks = 0; ks < 2; ++ks) xf[ks] = *(const LAS bf16x8*)(XC + (16 * mi + c) * 520 + 64 * h + 32 * ks + 8 * q);
;         f32x4 za[4], zx[4];
; #pragma unroll
;         for (int nf = 0; nf < 4; ++nf) { za[nf] = (f32x4){0.f, 0.f, 0.f, 0.f}; zx[nf] = za[nf];
;             za[nf] = mfma16(wa[nf][0], xf[0], za[nf]); za[nf] = mfma16(wa[nf][1], xf[1], za[nf]);
;             zx[nf] = mfma16(wx[nf][0], xf[0], zx[nf]); zx[nf] = mfma16(wx[nf][1], xf[1], zx[nf]); }
; #pragma unroll
;         for (int nf = 0; nf < 4; ++nf) {
;             const int jo = 16 * nf + 4 * q;
;             const bf16x4 xc4 = *(const LAS bf16x4*)(XC + (16 * mi + c) * 520 + 64 * h + jo);
;             const f32x4 zav = za[nf] + ba4[nf], zxv = zx[nf] + bx4[nf];
;             f32x4 av, uv;
; #pragma unroll
;             for (int r = 0; r < 4; ++r) {
;                 const float ra = sigmoidf_(zav[r]), ix = sigmoidf_(zxv[r]);
;                 const float la = ra * sp4[nf][r];
;                 av[r] = __expf(la);
;                 const float x2 = 2.0f * la;
;                 const float om = -x2 * (1.0f + x2 * (0.5f + x2 * (0.16666667f + x2 * (0.041666668f + x2 * (0.0083333338f + x2 * (0.0013888889f + x2 * 0.0001984127f))))));
;                 uv[r] = bf2f((bf16_t)xc4[r]) * ix * __builtin_amdgcn_sqrtf(fmaxf(om, 0.f));
;             }
;             *(LAS f32x4*)(STA + c * 68 + jo) = av; *(LAS f32x4*)(STU + c * 68 + jo) = uv;
	v_mul_f32_e32 v134, v184, v123
	v_exp_f32_e32 v123, v134
	s_nop 0
	v_fma_f32 v134, -v123, v123, 1.0
	v_max_f32_e32 v134, 0, v134
	v_sqrt_f32_e32 v145, v134
	v_pk_mul_f32 v[140:141], v[140:141], v[148:149]
	v_add_co_u32_e32 v148, vcc, s1, v136
	s_mov_b32 s1, 0x1875000
	s_nop 0
	v_addc_co_u32_e32 v149, vcc, 0, v137, vcc
	v_add_co_u32_e32 v146, vcc, s1, v136
	s_mov_b32 s1, 0x1874000
	s_nop 0
	v_addc_co_u32_e32 v147, vcc, 0, v137, vcc
	v_pk_mul_f32 v[208:209], v[140:141], v[144:145]
	v_add_co_u32_e32 v144, vcc, s1, v136
	s_mov_b32 s1, 0x1873000
	s_nop 0
	v_addc_co_u32_e32 v145, vcc, 0, v137, vcc
	v_add_co_u32_e32 v142, vcc, s1, v136
	s_mov_b32 s1, 0x1872000
	s_nop 0
	v_addc_co_u32_e32 v143, vcc, 0, v137, vcc
	v_add_co_u32_e32 v140, vcc, s1, v136
	s_mov_b32 s1, 0x1871000
	s_nop 0
	v_addc_co_u32_e32 v141, vcc, 0, v137, vcc
	v_add_co_u32_e32 v138, vcc, s1, v136
	s_mov_b32 s1, 0x1870000
	s_nop 0
	v_addc_co_u32_e32 v139, vcc, 0, v137, vcc
	v_add_co_u32_e32 v136, vcc, s1, v136
	global_load_ushort v205, v[148:149], off offset:2048
	global_load_ushort v201, v[148:149], off
	v_addc_co_u32_e32 v137, vcc, 0, v137, vcc
	global_load_ushort v203, v[146:147], off offset:2048
	global_load_ushort v202, v[146:147], off
	global_load_ushort v193, v[144:145], off offset:2048
	global_load_ushort v134, v[144:145], off
	global_load_ushort v195, v[142:143], off offset:2048
	global_load_ushort v194, v[142:143], off
	global_load_ushort v197, v[140:141], off offset:2048
	global_load_ushort v196, v[140:141], off
	global_load_ushort v198, v[138:139], off offset:2048
	global_load_ushort v199, v[138:139], off
	global_load_ushort v200, v[136:137], off offset:2048
	global_load_ushort v192, v[136:137], off
	ds_write_b128 v154, v[120:123]
	ds_write_b128 v154, v[206:209] offset:4352
	v_rcp_f32_e32 v122, v116
	v_rcp_f32_e32 v116, v112
	v_mul_f32_e32 v119, 0xbfb8aa3b, v119
	v_exp_f32_e32 v119, v119
	v_mul_f32_e32 v122, v183, v122
	v_exp_f32_e32 v112, v122
	s_nop 0
	v_fma_f32 v122, -v112, v112, 1.0
	v_rcp_f32_e32 v123, v117
	v_rcp_f32_e32 v117, v113
	v_add_f32_e32 v115, v47, v115
	v_add_f32_e32 v119, 1.0, v119
	v_mul_f32_e32 v123, v182, v123
	v_exp_f32_e32 v113, v123
	s_nop 0
	v_fma_f32 v123, -v113, v113, 1.0
	v_rcp_f32_e32 v152, v118
	v_rcp_f32_e32 v118, v114
	v_mul_f32_e32 v115, 0xbfb8aa3b, v115
	v_exp_f32_e32 v115, v115
	v_mul_f32_e32 v152, v175, v152
	v_exp_f32_e32 v114, v152
	s_nop 0
	v_fma_f32 v152, -v114, v114, 1.0
	v_rcp_f32_e32 v153, v119
	v_add_f32_e32 v115, 1.0, v115
	v_rcp_f32_e32 v119, v115
	ds_read_b64 v[120:121], v133 offset:32
	v_mul_f32_e32 v153, v174, v153
	v_exp_f32_e32 v115, v153
	v_add_f32_e32 v108, v64, v108
	v_fma_f32 v153, -v115, v115, 1.0
	v_mul_f32_e32 v108, 0xbfb8aa3b, v108
	v_max_f32_e32 v122, 0, v122
	v_max_f32_e32 v123, 0, v123
	v_max_f32_e32 v152, 0, v152
	v_max_f32_e32 v153, 0, v153
	v_exp_f32_e32 v108, v108
	v_sqrt_f32_e32 v122, v122
	v_sqrt_f32_e32 v123, v123
	v_sqrt_f32_e32 v152, v152
	v_sqrt_f32_e32 v153, v153
	s_waitcnt lgkmcnt(0)
	v_and_b32_e32 v179, 0xffff0000, v120
	v_lshlrev_b32_e32 v178, 16, v120
	v_and_b32_e32 v181, 0xffff0000, v121
	v_lshlrev_b32_e32 v180, 16, v121
	v_add_f32_e32 v104, v68, v104
	v_pk_mul_f32 v[118:119], v[118:119], v[180:181]
	v_pk_mul_f32 v[116:117], v[116:117], v[178:179]
	v_add_f32_e32 v108, 1.0, v108
	v_mul_f32_e32 v104, 0xbfb8aa3b, v104
	v_pk_mul_f32 v[116:117], v[116:117], v[122:123]
	v_pk_mul_f32 v[118:119], v[118:119], v[152:153]
	ds_write_b128 v154, v[112:115] offset:64
	ds_write_b128 v154, v[116:119] offset:4416
	v_rcp_f32_e32 v114, v108
	v_exp_f32_e32 v104, v104
	v_add_f32_e32 v109, v65, v109
	v_mul_f32_e32 v109, 0xbfb8aa3b, v109
	v_mul_f32_e32 v114, v173, v114
	v_add_f32_e32 v104, 1.0, v104
	v_rcp_f32_e32 v108, v104
	v_exp_f32_e32 v104, v114
	v_exp_f32_e32 v109, v109
	v_add_f32_e32 v105, v69, v105
	v_add_f32_e32 v109, 1.0, v109
	v_mul_f32_e32 v105, 0xbfb8aa3b, v105
	v_fma_f32 v114, -v104, v104, 1.0
	v_rcp_f32_e32 v115, v109
	v_exp_f32_e32 v105, v105
	v_add_f32_e32 v110, v66, v110
	v_mul_f32_e32 v110, 0xbfb8aa3b, v110
	v_mul_f32_e32 v115, v172, v115
	v_add_f32_e32 v105, 1.0, v105
	v_rcp_f32_e32 v109, v105
	v_exp_f32_e32 v105, v115
	v_exp_f32_e32 v110, v110
	v_add_f32_e32 v106, v70, v106
	v_add_f32_e32 v110, 1.0, v110
	v_mul_f32_e32 v106, 0xbfb8aa3b, v106
	v_fma_f32 v115, -v105, v105, 1.0
	v_rcp_f32_e32 v116, v110
	v_exp_f32_e32 v106, v106
	v_add_f32_e32 v111, v67, v111
	v_mul_f32_e32 v111, 0xbfb8aa3b, v111
	v_mul_f32_e32 v116, v171, v116
	v_add_f32_e32 v106, 1.0, v106
	v_rcp_f32_e32 v110, v106
	v_exp_f32_e32 v106, v116
	v_exp_f32_e32 v111, v111
	v_add_f32_e32 v107, v71, v107
	v_add_f32_e32 v111, 1.0, v111
	v_mul_f32_e32 v107, 0xbfb8aa3b, v107
	v_fma_f32 v116, -v106, v106, 1.0
	v_rcp_f32_e32 v117, v111
	v_exp_f32_e32 v107, v107
	ds_read_b64 v[112:113], v133 offset:64
	s_waitcnt vmcnt(17)
	v_add_f32_e32 v100, v88, v100
	v_mul_f32_e32 v117, v170, v117
	v_add_f32_e32 v107, 1.0, v107
	v_rcp_f32_e32 v111, v107
	v_exp_f32_e32 v107, v117
	s_nop 0
	v_fma_f32 v117, -v107, v107, 1.0
	v_mul_f32_e32 v100, 0xbfb8aa3b, v100
	v_max_f32_e32 v114, 0, v114
	v_max_f32_e32 v115, 0, v115
	v_max_f32_e32 v116, 0, v116
	v_max_f32_e32 v117, 0, v117
	v_exp_f32_e32 v100, v100
	v_sqrt_f32_e32 v114, v114
	v_sqrt_f32_e32 v115, v115
	v_sqrt_f32_e32 v116, v116
	v_sqrt_f32_e32 v117, v117
	s_waitcnt lgkmcnt(0)
	v_and_b32_e32 v119, 0xffff0000, v112
	v_lshlrev_b32_e32 v118, 16, v112
	v_and_b32_e32 v121, 0xffff0000, v113
	v_lshlrev_b32_e32 v120, 16, v113
	s_waitcnt vmcnt(16)
; #define LAS __attribute__((address_space(3)))
; __device__ __forceinline__ float bf2f(bf16_t b) { return __uint_as_float(((unsigned)b) << 16); }
; __device__ __forceinline__ unsigned cvtpk(float lo, float hi) { const f32x2 v = (f32x2){lo, hi}; const bf16v2 b = __builtin_convertvector(v, bf16v2); return __builtin_bit_cast(unsigned, b); }
; __device__ __forceinline__ float sigmoidf_(float x) { return __builtin_amdgcn_rcpf(1.0f + __expf(-x)); }
; template <int DIR> __device__ __forceinline__ void lru_dir(const Params& p, int l, int n, int h, int lane, LAS bf16_t* XC, LAS float* STA, LAS float* STU) {
;     ...
;         for (int nf = 0; nf < 4; ++nf) {
;             const int jo = 16 * nf + 4 * q;
;             const bf16x4 xc4 = *(const LAS bf16x4*)(XC + (16 * mi + c) * 520 + 64 * h + jo);
;             const f32x4 zav = za[nf] + ba4[nf], zxv = zx[nf] + bx4[nf];
;             f32x4 av, uv;
; #pragma unroll
;             for (int r = 0; r < 4; ++r) {
;                 const float ra = sigmoidf_(zav[r]), ix = sigmoidf_(zxv[r]);
;                 const float la = ra * sp4[nf][r];
;                 av[r] = __expf(la);
;                 const float x2 = 2.0f * la;
;                 const float om = -x2 * (1.0f + x2 * (0.5f + x2 * (0.16666667f + x2 * (0.041666668f + x2 * (0.0083333338f + x2 * (0.0013888889f + x2 * 0.0001984127f))))));
;                 uv[r] = bf2f((bf16_t)xc4[r]) * ix * __builtin_amdgcn_sqrtf(fmaxf(om, 0.f));
;             }
;             *(LAS f32x4*)(STA + c * 68 + jo) = av; *(LAS f32x4*)(STU + c * 68 + jo) = uv;
;         }
;         LDS_FENCE();
;         float aa[16], uu[16];
; #pragma unroll
;         for (int s = 0; s < 16; ++s) { aa[s] = STA[s * 68 + j]; uu[s] = STU[s * 68 + j]; }
;         LDS_FENCE();
; #pragma unroll
;         for (int s = 0; s < 16; ++s) {
;             const int tl = DIR == 0 ? s : 15 - s;
;             hcar = aa[tl] * hcar + uu[tl]; P *= aa[tl];
;             const size_t row = (size_t)(t0 + 16 * mi + tl);
;             if (DIR == 0) { const unsigned w = cvtpk(hcar, P); y[row * D + 64 * h + j] = (bf16_t)(w & 0xffffu); y[row * D + 512 + 64 * h + j] = (bf16_t)(w >> 16); }
;             else { const unsigned w = cvtpk(bf2f(hfp[tl]) + hcar, P); y[row * D + 64 * h + j] = (bf16_t)(w & 0xffffu); __builtin_nontemporal_store((bf16_t)(w >> 16), PB + row * 512 + 64 * h + j); }
	v_add_f32_e32 v96, v92, v96
	v_pk_mul_f32 v[110:111], v[110:111], v[120:121]
	v_pk_mul_f32 v[108:109], v[108:109], v[118:119]
	v_add_f32_e32 v100, 1.0, v100
	v_mul_f32_e32 v96, 0xbfb8aa3b, v96
	v_pk_mul_f32 v[108:109], v[108:109], v[114:115]
	v_pk_mul_f32 v[110:111], v[110:111], v[116:117]
	ds_write_b128 v154, v[104:107] offset:128
	ds_write_b128 v154, v[108:111] offset:4480
	v_rcp_f32_e32 v106, v100
	v_exp_f32_e32 v96, v96
	v_add_f32_e32 v101, v89, v101
	v_mul_f32_e32 v101, 0xbfb8aa3b, v101
	v_mul_f32_e32 v106, v169, v106
	v_add_f32_e32 v96, 1.0, v96
	v_rcp_f32_e32 v100, v96
	v_exp_f32_e32 v96, v106
	v_exp_f32_e32 v101, v101
	v_add_f32_e32 v97, v93, v97
	v_add_f32_e32 v101, 1.0, v101
	v_mul_f32_e32 v97, 0xbfb8aa3b, v97
	v_fma_f32 v106, -v96, v96, 1.0
	v_rcp_f32_e32 v107, v101
	v_exp_f32_e32 v97, v97
	v_add_f32_e32 v102, v90, v102
	v_mul_f32_e32 v102, 0xbfb8aa3b, v102
	v_mul_f32_e32 v107, v168, v107
	v_add_f32_e32 v97, 1.0, v97
	v_rcp_f32_e32 v101, v97
	v_exp_f32_e32 v97, v107
	v_exp_f32_e32 v102, v102
	v_add_f32_e32 v98, v94, v98
	v_add_f32_e32 v102, 1.0, v102
	v_mul_f32_e32 v98, 0xbfb8aa3b, v98
	v_fma_f32 v107, -v97, v97, 1.0
	v_rcp_f32_e32 v108, v102
	v_exp_f32_e32 v98, v98
	v_add_f32_e32 v103, v91, v103
	v_mul_f32_e32 v103, 0xbfb8aa3b, v103
	v_mul_f32_e32 v108, v167, v108
	v_add_f32_e32 v98, 1.0, v98
	v_rcp_f32_e32 v102, v98
	v_exp_f32_e32 v98, v108
	v_exp_f32_e32 v103, v103
	v_add_f32_e32 v99, v95, v99
	v_add_f32_e32 v103, 1.0, v103
	v_mul_f32_e32 v99, 0xbfb8aa3b, v99
	v_fma_f32 v108, -v98, v98, 1.0
	v_rcp_f32_e32 v109, v103
	v_exp_f32_e32 v99, v99
	ds_read_b64 v[104:105], v133 offset:96
	v_max_f32_e32 v106, 0, v106
	v_mul_f32_e32 v109, v190, v109
	v_add_f32_e32 v99, 1.0, v99
	v_rcp_f32_e32 v103, v99
	v_exp_f32_e32 v99, v109
	s_nop 0
	v_fma_f32 v109, -v99, v99, 1.0
	v_max_f32_e32 v107, 0, v107
	v_max_f32_e32 v108, 0, v108
	v_max_f32_e32 v109, 0, v109
	v_sqrt_f32_e32 v106, v106
	v_sqrt_f32_e32 v107, v107
	v_sqrt_f32_e32 v108, v108
	v_sqrt_f32_e32 v109, v109
	s_waitcnt lgkmcnt(0)
	v_and_b32_e32 v111, 0xffff0000, v104
	v_lshlrev_b32_e32 v110, 16, v104
	v_and_b32_e32 v113, 0xffff0000, v105
	v_lshlrev_b32_e32 v112, 16, v105
	v_pk_mul_f32 v[102:103], v[102:103], v[112:113]
	v_pk_mul_f32 v[100:101], v[100:101], v[110:111]
	v_pk_mul_f32 v[102:103], v[102:103], v[108:109]
	v_pk_mul_f32 v[100:101], v[100:101], v[106:107]
	ds_write_b128 v154, v[96:99] offset:192
	ds_write_b128 v154, v[100:103] offset:4544
	s_waitcnt lgkmcnt(0)
	ds_read2_b32 v[152:153], v164 offset0:184 offset1:252
	ds_read2_b32 v[122:123], v166 offset0:120 offset1:188
	s_waitcnt vmcnt(14)
	v_lshlrev_b32_e32 v180, 16, v204
	s_mov_b32 s1, 0xd3e7000
	s_waitcnt lgkmcnt(1)
	v_mov_b32_e32 v211, v152
	s_waitcnt lgkmcnt(0)
	v_fma_f32 v178, v132, v153, v123
	ds_read2_b32 v[98:99], v155 offset1:68
	ds_read2_b32 v[96:97], v156 offset0:64 offset1:132
	ds_read2_b32 v[100:101], v155 offset0:136 offset1:204
	ds_read2_b32 v[102:103], v157 offset0:72 offset1:140
	ds_read2_b32 v[104:105], v158 offset0:16 offset1:84
	ds_read2_b32 v[108:109], v159 offset0:80 offset1:148
	ds_read2_b32 v[106:107], v158 offset0:152 offset1:220
	ds_read2_b32 v[112:113], v160 offset0:88 offset1:156
	ds_read2_b32 v[110:111], v161 offset0:32 offset1:100
	ds_read2_b32 v[114:115], v162 offset0:96 offset1:164
	ds_read2_b32 v[116:117], v161 offset0:168 offset1:236
	ds_read2_b32 v[118:119], v163 offset0:104 offset1:172
	ds_read2_b32 v[120:121], v164 offset0:48 offset1:116
	ds_read2_b32 v[132:133], v165 offset0:112 offset1:180
	v_fmac_f32_e32 v122, v152, v178
	v_mov_b32_e32 v123, v135
	v_lshlrev_b32_e32 v135, 16, v189
	v_add_f32_e32 v181, v122, v180
	s_waitcnt vmcnt(13)
	v_lshlrev_b32_e32 v180, 16, v205
	s_waitcnt lgkmcnt(1)
	v_mov_b32_e32 v204, v121
	v_mov_b32_e32 v205, v153
	v_add_f32_e32 v135, v178, v135
	v_lshl_add_u64 v[178:179], v[128:129], 0, v[176:177]
	v_pk_mul_f32 v[206:207], v[204:205], v[122:123]
	s_waitcnt lgkmcnt(0)
	v_mov_b32_e32 v210, v133
	v_add_co_u32_e32 v208, vcc, s1, v178
	v_pk_mul_f32 v[152:153], v[210:211], v[206:207]
	v_cvt_pk_bf16_f32 v135, v135, v207
	v_addc_co_u32_e32 v209, vcc, 0, v179, vcc
	v_pk_fma_f32 v[122:123], v[204:205], v[122:123], v[210:211]
	v_cvt_pk_bf16_f32 v133, v181, v153
	v_mov_b32_e32 v181, v121
	s_waitcnt lgkmcnt(0)
	global_store_short v[150:151], v135, off offset:2048
	global_store_short_d16_hi v[208:209], v135, off offset:3072 nt
	global_store_short v[150:151], v133, off
	global_store_short_d16_hi v[208:209], v133, off offset:2048 nt
	v_pk_add_f32 v[150:151], v[122:123], v[180:181]
	v_pk_mul_f32 v[152:153], v[152:153], v[180:181]
	v_fmac_f32_e32 v132, v120, v122
	v_cvt_pk_bf16_f32 v121, v150, v153
	global_store_short v[148:149], v121, off offset:2048
	global_store_short_d16_hi v[208:209], v121, off offset:1024 nt
	s_waitcnt vmcnt(18)
	v_lshlrev_b32_e32 v121, 16, v201
	v_fmac_f32_e32 v119, v117, v132
	v_add_f32_e32 v123, v132, v121
	s_waitcnt vmcnt(17)
	v_lshlrev_b32_e32 v121, 16, v203
	v_mov_b32_e32 v132, v116
	v_mov_b32_e32 v133, v120
	v_mov_b32_e32 v152, v119
	v_add_f32_e32 v135, v119, v121
	v_pk_mul_f32 v[120:121], v[132:133], v[152:153]
	s_mov_b32 s1, 0xd3e6000
	v_cvt_pk_bf16_f32 v119, v123, v121
	global_store_short v[148:149], v119, off
	global_store_short_d16_hi v[208:209], v119, off nt
	v_mov_b32_e32 v119, v117
	v_pk_fma_f32 v[132:133], v[132:133], v[152:153], v[118:119]
	v_pk_mul_f32 v[118:119], v[118:119], v[120:121]
	v_add_co_u32_e32 v120, vcc, s1, v178
	s_waitcnt vmcnt(18)
; __device__ __forceinline__ float bf2f(bf16_t b) { return __uint_as_float(((unsigned)b) << 16); }
; __device__ __forceinline__ unsigned cvtpk(float lo, float hi) { const f32x2 v = (f32x2){lo, hi}; const bf16v2 b = __builtin_convertvector(v, bf16v2); return __builtin_bit_cast(unsigned, b); }
; __device__ __forceinline__ int obid() { int t = blockIdx.x; asm volatile("" : "+s"(t)); return t; }
; template <int DIR> __device__ __forceinline__ void lru_dir(const Params& p, int l, int n, int h, int lane, LAS bf16_t* XC, LAS float* STA, LAS float* STU) {
;     ...
; #pragma unroll
;         for (int s = 0; s < 16; ++s) {
;             const int tl = DIR == 0 ? s : 15 - s;
;             hcar = aa[tl] * hcar + uu[tl]; P *= aa[tl];
;             const size_t row = (size_t)(t0 + 16 * mi + tl);
;             if (DIR == 0) { const unsigned w = cvtpk(hcar, P); y[row * D + 64 * h + j] = (bf16_t)(w & 0xffffu); y[row * D + 512 + 64 * h + j] = (bf16_t)(w >> 16); }
;             else { const unsigned w = cvtpk(bf2f(hfp[tl]) + hcar, P); y[row * D + 64 * h + j] = (bf16_t)(w & 0xffffu); __builtin_nontemporal_store((bf16_t)(w >> 16), PB + row * 512 + 64 * h + j); }
;         }
;     }
;     Aprod[(size_t)(DIR * NCH + n) * 512 + 64 * h + j] = P; Hend[(size_t)(DIR * NCH + n) * 512 + 64 * h + j] = hcar;
; }
; __global__ void __launch_bounds__(NTHR, 2) mk_fwd(Params p) {
;     ...
;         case 2: for (int n = obid(); n < NCH; n += gridDim.x) mixer_lru<0>(p, l, n, lds);
;                 for (int n = obid(); n < NCH; n += gridDim.x) mixer_gla<0>(p, l, n, lds); break;
	v_lshlrev_b32_e32 v122, 16, v202
	v_mov_b32_e32 v118, v132
	v_cvt_pk_bf16_f32 v117, v135, v119
	v_addc_co_u32_e32 v121, vcc, 0, v179, vcc
	v_mov_b32_e32 v123, v116
	global_store_short v[146:147], v117, off offset:2048
	global_store_short_d16_hi v[120:121], v117, off offset:3072 nt
	v_pk_add_f32 v[116:117], v[132:133], v[122:123]
	v_pk_mul_f32 v[118:119], v[118:119], v[122:123]
	v_fma_f32 v115, v111, v132, v115
	v_cvt_pk_bf16_f32 v116, v116, v119
	global_store_short v[146:147], v116, off
	global_store_short_d16_hi v[120:121], v116, off offset:2048 nt
	s_waitcnt vmcnt(21)
	v_lshlrev_b32_e32 v116, 16, v193
	v_add_f32_e32 v116, v115, v116
	v_fmac_f32_e32 v114, v110, v115
	s_waitcnt vmcnt(20)
	v_lshlrev_b32_e32 v115, 16, v134
	v_add_f32_e32 v117, v114, v115
	v_fma_f32 v113, v107, v114, v113
	s_waitcnt vmcnt(19)
	v_lshlrev_b32_e32 v114, 16, v195
	v_add_f32_e32 v122, v113, v114
	v_fmac_f32_e32 v112, v106, v113
	s_waitcnt vmcnt(18)
	v_lshlrev_b32_e32 v113, 16, v194
	v_add_f32_e32 v123, v112, v113
	v_fmac_f32_e32 v109, v105, v112
	s_waitcnt vmcnt(17)
	v_lshlrev_b32_e32 v112, 16, v197
	v_add_f32_e32 v132, v109, v112
	v_mov_b32_e32 v112, v104
	v_mov_b32_e32 v113, v111
	v_mov_b32_e32 v118, v109
	v_pk_mul_f32 v[114:115], v[112:113], v[118:119]
	s_mov_b32 s1, 0xd3e5000
	v_cvt_pk_bf16_f32 v109, v116, v115
	global_store_short v[144:145], v109, off offset:2048
	global_store_short_d16_hi v[120:121], v109, off offset:1024 nt
	v_mov_b32_e32 v109, v110
	v_pk_fma_f32 v[110:111], v[112:113], v[118:119], v[108:109]
	v_pk_mul_f32 v[108:109], v[108:109], v[114:115]
	v_add_co_u32_e32 v114, vcc, s1, v178
	v_cvt_pk_bf16_f32 v108, v117, v109
	v_mov_b32_e32 v111, v109
	global_store_short v[144:145], v108, off
	global_store_short_d16_hi v[120:121], v108, off nt
	v_mov_b32_e32 v108, v101
	v_mov_b32_e32 v109, v107
	v_pk_mul_f32 v[112:113], v[108:109], v[110:111]
	v_addc_co_u32_e32 v115, vcc, 0, v179, vcc
	v_cvt_pk_bf16_f32 v107, v122, v113
	v_mov_b32_e32 v116, v103
	v_mov_b32_e32 v117, v106
	global_store_short v[142:143], v107, off offset:2048
	global_store_short_d16_hi v[114:115], v107, off offset:3072 nt
	v_pk_fma_f32 v[106:107], v[108:109], v[110:111], v[116:117]
	v_pk_mul_f32 v[108:109], v[116:117], v[112:113]
	s_waitcnt vmcnt(22)
	v_lshlrev_b32_e32 v133, 16, v196
	v_mov_b32_e32 v107, v109
	v_cvt_pk_bf16_f32 v103, v123, v109
	v_mov_b32_e32 v108, v100
	v_mov_b32_e32 v109, v105
	v_pk_mul_f32 v[112:113], v[108:109], v[106:107]
	global_store_short v[142:143], v103, off
	global_store_short_d16_hi v[114:115], v103, off offset:2048 nt
	v_cvt_pk_bf16_f32 v103, v132, v113
	global_store_short v[140:141], v103, off offset:2048
	global_store_short_d16_hi v[114:115], v103, off offset:1024 nt
	v_mov_b32_e32 v103, v104
	v_add_f32_e32 v110, v110, v133
	v_pk_fma_f32 v[104:105], v[108:109], v[106:107], v[102:103]
	v_pk_mul_f32 v[102:103], v[102:103], v[112:113]
	s_waitcnt vmcnt(25)
	v_lshlrev_b32_e32 v134, 16, v198
	v_cvt_pk_bf16_f32 v102, v110, v103
	v_mov_b32_e32 v105, v103
	global_store_short v[140:141], v102, off
	global_store_short_d16_hi v[114:115], v102, off nt
	v_mov_b32_e32 v102, v99
	v_mov_b32_e32 v103, v101
	v_add_f32_e32 v108, v106, v134
	v_pk_mul_f32 v[106:107], v[102:103], v[104:105]
	s_mov_b32 s1, 0xd3e4000
	v_cvt_pk_bf16_f32 v101, v108, v107
	v_add_co_u32_e32 v108, vcc, s1, v178
	s_waitcnt vmcnt(26)
	v_lshlrev_b32_e32 v135, 16, v199
	v_addc_co_u32_e32 v109, vcc, 0, v179, vcc
	v_mov_b32_e32 v110, v97
	v_mov_b32_e32 v111, v100
	global_store_short v[138:139], v101, off offset:2048
	global_store_short_d16_hi v[108:109], v101, off offset:3072 nt
	v_add_f32_e32 v112, v104, v135
	v_pk_fma_f32 v[100:101], v[102:103], v[104:105], v[110:111]
	v_pk_mul_f32 v[102:103], v[110:111], v[106:107]
	s_waitcnt vmcnt(27)
	v_lshlrev_b32_e32 v146, 16, v200
	v_mov_b32_e32 v101, v103
	v_cvt_pk_bf16_f32 v97, v112, v103
	global_store_short v[138:139], v97, off
	global_store_short_d16_hi v[108:109], v97, off offset:2048 nt
	v_add_f32_e32 v97, v100, v146
	v_pk_mul_f32 v[102:103], v[98:99], v[100:101]
	v_lshl_add_u64 v[128:129], v[128:129], 0, s[28:29]
	v_cvt_pk_bf16_f32 v97, v97, v103
	global_store_short v[136:137], v97, off offset:2048
	global_store_short_d16_hi v[108:109], v97, off offset:1024 nt
	v_mov_b32_e32 v97, v98
	v_pk_fma_f32 v[132:133], v[98:99], v[100:101], v[96:97]
	v_pk_mul_f32 v[134:135], v[96:97], v[102:103]
	s_waitcnt vmcnt(30)
	v_lshlrev_b32_e32 v96, 16, v192
	s_movk_i32 s28, 0x8000
	v_add_f32_e32 v96, v132, v96
	s_mov_b32 s29, -1
	v_cvt_pk_bf16_f32 v96, v96, v135
	v_lshl_add_u64 v[130:131], v[130:131], 0, s[28:29]
	global_store_short v[136:137], v96, off
	global_store_short_d16_hi v[108:109], v96, off nt
	s_cbranch_scc1 .LBB0_323
	s_lshl_b64 s[0:1], s[4:5], 9
	s_add_u32 s0, s0, 0x20000
	s_addc_u32 s1, s1, 0
	v_lshl_add_u64 v[0:1], s[0:1], 0, v[124:125]
	v_or_b32_e32 v0, v0, v126
	v_readlane_b32 s0, v254, 11
	v_lshlrev_b64 v[0:1], 2, v[0:1]
	v_readlane_b32 s1, v254, 12
	s_nop 1
	v_lshl_add_u64 v[2:3], s[0:1], 0, v[0:1]
	v_readlane_b32 s0, v254, 13
	v_readlane_b32 s1, v254, 14
	global_store_dword v[2:3], v135, off
	s_nop 0
	v_lshl_add_u64 v[0:1], s[0:1], 0, v[0:1]
	v_readlane_b32 s0, v255, 8
	v_readlane_b32 s1, v255, 9
	global_store_dword v[0:1], v132, off
	s_barrier
	s_load_dword s0, s[0:1], 0x0
	s_waitcnt lgkmcnt(0)
	s_add_i32 s4, s0, s4
	s_cmpk_gt_i32 s4, 0xff
	s_cbranch_scc0 .LBB0_192

; __device__ __forceinline__ f32x4 mfma16(bf16x8 a, bf16x8 b, f32x4 c) { return __builtin_amdgcn_mfma_f32_16x16x32_bf16(a, b, c, 0, 0, 0); }
; template <int MODE> __device__ void mixer_gla(const Params& p, int l, int n, LAS unsigned char* lds) {
;     ...
;             bf16x8 lrf[4], gwf[4]; float bgv[4];
; #pragma unroll
;             for (int tt = 0; tt < 4; ++tt) { lrf[tt] = (bf16x8){0, 0, 0, 0, 0, 0, 0, 0}; if (q < 2) lrf[tt] = *(const bf16x8*)(proj + (size_t)(t0 + 16 * tt + c) * DINP + 2560 + dir * 16 + 8 * q); }
; #pragma unroll
;             for (int ef = 0; ef < 4; ++ef) { gwf[ef] = *(const bf16x8*)(GW + (size_t)(dir * 256 + 64 * h + SIGC(ef, c)) * 32 + 8 * q); bgv[ef] = p.in[13][(size_t)(l * 2 + dir) * 256 + 64 * h + SIGC(ef, c)]; }
; #pragma unroll
;             for (int ef = 0; ef < 4; ++ef) { tot[ef] = 0.f;
; #pragma unroll
;                 for (int ks = 0; ks < 2; ++ks) { f32x4 la2[2];
; #pragma unroll
;                     for (int t2 = 0; t2 < 2; ++t2) { const f32x4 z = mfma16(lrf[2 * ks + t2], gwf[ef], zero4);
; #pragma unroll
;                         for (int r = 0; r < 4; ++r) { const float zz = z[r] + bgv[ef]; const float la = (fminf(zz, 0.f) - __logf(1.0f + __expf(-fabsf(zz)))) * (1.0f / 16.0f); la2[t2][r] = la; tot[ef] += la; } }
;                     laop[ef][ks] = pack8(la2[0], la2[1]); __builtin_amdgcn_sched_barrier(0); } }
.LBB0_338:
	s_or_b64 exec, exec, s[0:1]
	s_lshl_b32 s4, s5, 8
	v_add_u32_e32 v30, s4, v88
	v_or_b32_e32 v16, v30, v90
	v_ashrrev_i32_e32 v17, 31, v16
	v_lshlrev_b64 v[16:17], 6, v[16:17]
	v_lshl_add_u64 v[16:17], v[92:93], 0, v[16:17]
	s_or_b32 s0, s5, s13
	global_load_dwordx4 v[24:27], v[16:17], off
	s_ashr_i32 s1, s0, 31
	s_lshl_b64 s[0:1], s[0:1], 10
	v_lshl_add_u64 v[28:29], v[114:115], 0, s[0:1]
	global_load_dword v40, v[28:29], off
	v_or_b32_e32 v16, v30, v117
	v_or_b32_e32 v20, v30, v118
	v_or_b32_e32 v30, v30, v119
	v_ashrrev_i32_e32 v17, 31, v16
	v_ashrrev_i32_e32 v21, 31, v20
	v_ashrrev_i32_e32 v31, 31, v30
	v_lshlrev_b64 v[16:17], 6, v[16:17]
	v_lshlrev_b64 v[20:21], 6, v[20:21]
	v_lshlrev_b64 v[30:31], 6, v[30:31]
	v_lshl_add_u64 v[16:17], v[92:93], 0, v[16:17]
	v_lshl_add_u64 v[20:21], v[92:93], 0, v[20:21]
	v_lshl_add_u64 v[30:31], v[92:93], 0, v[30:31]
	global_load_dwordx4 v[16:19], v[16:17], off
	s_nop 0
	global_load_dword v78, v[28:29], off offset:16
	s_nop 0
	global_load_dwordx4 v[20:23], v[20:21], off
	s_nop 0
	global_load_dword v77, v[28:29], off offset:128
	global_load_dwordx4 v[44:47], v[30:31], off
	global_load_dword v76, v[28:29], off offset:144
	s_waitcnt vmcnt(7)
	v_mfma_f32_16x16x32_bf16 v[28:31], v[12:15], v[24:27], 0
	s_waitcnt vmcnt(6)
	s_nop 6
	v_add_f32_e32 v41, v40, v28
	v_min_f32_e32 v28, 0, v41
	v_mul_f32_e64 v41, |v41|, s33
	v_exp_f32_e32 v41, v41
	v_add_f32_e32 v31, v40, v31
	v_add_f32_e32 v41, 1.0, v41
	v_log_f32_e32 v41, v41
	s_nop 0
	v_mul_f32_e32 v42, 0x3f317217, v41
	v_add_f32_e32 v41, v40, v29
	v_min_f32_e32 v29, 0, v41
	v_mul_f32_e64 v41, |v41|, s33
	v_exp_f32_e32 v41, v41
	s_nop 0
	v_add_f32_e32 v41, 1.0, v41
	v_log_f32_e32 v41, v41
	s_nop 0
	v_mul_f32_e32 v43, 0x3f317217, v41
	v_pk_add_f32 v[28:29], v[28:29], v[42:43] neg_lo:[0,1] neg_hi:[0,1]
	s_nop 0
	v_pk_mul_f32 v[68:69], v[28:29], s[50:51] op_sel_hi:[1,0]
	v_add_f32_e32 v29, v40, v30
	v_add_f32_e32 v28, 0, v68
	v_add_f32_e32 v41, v69, v28
	v_min_f32_e32 v28, 0, v29
	v_mul_f32_e64 v29, |v29|, s33
	v_exp_f32_e32 v29, v29
	s_nop 0
	v_add_f32_e32 v29, 1.0, v29
	v_log_f32_e32 v29, v29
	s_nop 0
	v_mul_f32_e32 v30, 0x3f317217, v29
	v_min_f32_e32 v29, 0, v31
	v_mul_f32_e64 v31, |v31|, s33
	v_exp_f32_e32 v31, v31
	s_nop 0
	v_add_f32_e32 v31, 1.0, v31
	v_log_f32_e32 v31, v31
	s_nop 0
	v_mul_f32_e32 v42, 0x3f317217, v31
	v_mov_b32_e32 v31, v42
	v_pk_add_f32 v[28:29], v[28:29], v[30:31] neg_lo:[0,1] neg_hi:[0,1]
	s_nop 0
	v_pk_mul_f32 v[70:71], v[28:29], s[50:51] op_sel_hi:[1,0]
	s_nop 0
	v_add_f32_e32 v28, v70, v41
	v_add_f32_e32 v41, v71, v28
	v_mfma_f32_16x16x32_bf16 v[28:31], v[8:11], v[24:27], 0
	s_nop 7
	v_add_f32_e32 v42, v40, v28
	v_min_f32_e32 v28, 0, v42
	v_mul_f32_e64 v42, |v42|, s33
	v_exp_f32_e32 v42, v42
	v_add_f32_e32 v31, v40, v31
	v_add_f32_e32 v42, 1.0, v42
	v_log_f32_e32 v42, v42
	s_nop 0
	v_mul_f32_e32 v43, 0x3f317217, v42
	v_mov_b32_e32 v42, v43
	v_add_f32_e32 v43, v40, v29
	v_min_f32_e32 v29, 0, v43
	v_mul_f32_e64 v43, |v43|, s33
	v_exp_f32_e32 v43, v43
	s_nop 0
	v_add_f32_e32 v43, 1.0, v43
	v_log_f32_e32 v43, v43
	s_nop 0
	v_mul_f32_e32 v48, 0x3f317217, v43
	v_mov_b32_e32 v43, v48
	v_pk_add_f32 v[28:29], v[28:29], v[42:43] neg_lo:[0,1] neg_hi:[0,1]
	s_nop 0
	v_pk_mul_f32 v[72:73], v[28:29], s[50:51] op_sel_hi:[1,0]
	v_add_f32_e32 v29, v40, v30
	v_add_f32_e32 v28, v72, v41
	v_add_f32_e32 v41, v73, v28
	v_min_f32_e32 v28, 0, v29
	v_mul_f32_e64 v29, |v29|, s33
	v_exp_f32_e32 v29, v29
	s_nop 0
	v_add_f32_e32 v29, 1.0, v29
	v_log_f32_e32 v29, v29
	s_nop 0
	v_mul_f32_e32 v30, 0x3f317217, v29
	v_min_f32_e32 v29, 0, v31
	v_mul_f32_e64 v31, |v31|, s33
	v_exp_f32_e32 v31, v31
	s_nop 0
	v_add_f32_e32 v31, 1.0, v31
	v_log_f32_e32 v31, v31
	s_nop 0
	v_mul_f32_e32 v42, 0x3f317217, v31
	v_mov_b32_e32 v31, v42
	v_pk_add_f32 v[28:29], v[28:29], v[30:31] neg_lo:[0,1] neg_hi:[0,1]
	s_nop 0
	v_pk_mul_f32 v[74:75], v[28:29], s[50:51] op_sel_hi:[1,0]
	s_nop 0
	v_add_f32_e32 v28, v74, v41
	v_add_f32_e32 v41, v75, v28
	v_mfma_f32_16x16x32_bf16 v[28:31], v[36:39], v[24:27], 0
	v_mfma_f32_16x16x32_bf16 v[24:27], v[32:35], v[24:27], 0
	s_nop 6
	v_add_f32_e32 v42, v40, v28
	v_min_f32_e32 v28, 0, v42
	v_mul_f32_e64 v42, |v42|, s33
	v_exp_f32_e32 v42, v42
	v_add_f32_e32 v31, v40, v31
	v_add_f32_e32 v27, v40, v27
	v_add_f32_e32 v42, 1.0, v42
	v_log_f32_e32 v42, v42
	s_nop 0
	v_mul_f32_e32 v43, 0x3f317217, v42
	v_mov_b32_e32 v42, v43
	v_add_f32_e32 v43, v40, v29
	v_min_f32_e32 v29, 0, v43
	v_mul_f32_e64 v43, |v43|, s33
	v_exp_f32_e32 v43, v43
	s_nop 0
	v_add_f32_e32 v43, 1.0, v43
	v_log_f32_e32 v43, v43
	s_nop 0
	v_mul_f32_e32 v48, 0x3f317217, v43
	v_mov_b32_e32 v43, v48
	v_pk_add_f32 v[28:29], v[28:29], v[42:43] neg_lo:[0,1] neg_hi:[0,1]
	s_nop 0
	v_pk_mul_f32 v[80:81], v[28:29], s[50:51] op_sel_hi:[1,0]
	v_add_f32_e32 v29, v40, v30
	v_add_f32_e32 v28, v80, v41
	v_add_f32_e32 v41, v81, v28
	v_min_f32_e32 v28, 0, v29
	v_mul_f32_e64 v29, |v29|, s33
	v_exp_f32_e32 v29, v29
	s_nop 0
	v_add_f32_e32 v29, 1.0, v29
	v_log_f32_e32 v29, v29
	s_nop 0
	v_mul_f32_e32 v30, 0x3f317217, v29
	v_min_f32_e32 v29, 0, v31
	v_mul_f32_e64 v31, |v31|, s33
	v_exp_f32_e32 v31, v31
	s_nop 0
	v_add_f32_e32 v31, 1.0, v31
	v_log_f32_e32 v31, v31
	s_nop 0
	v_mul_f32_e32 v42, 0x3f317217, v31
	v_mov_b32_e32 v31, v42
	v_pk_add_f32 v[28:29], v[28:29], v[30:31] neg_lo:[0,1] neg_hi:[0,1]
	s_nop 0
	v_pk_mul_f32 v[82:83], v[28:29], s[50:51] op_sel_hi:[1,0]
	s_nop 0
	v_add_f32_e32 v28, v82, v41
	v_add_f32_e32 v30, v83, v28
	v_add_f32_e32 v28, v40, v24
	v_min_f32_e32 v24, 0, v28
	v_mul_f32_e64 v28, |v28|, s33
	v_exp_f32_e32 v28, v28
	s_nop 0
	v_add_f32_e32 v28, 1.0, v28
	v_log_f32_e32 v28, v28
	s_nop 0
	v_mul_f32_e32 v29, 0x3f317217, v28
	v_mov_b32_e32 v28, v29
	v_add_f32_e32 v29, v40, v25
	v_min_f32_e32 v25, 0, v29
	v_mul_f32_e64 v29, |v29|, s33
	v_exp_f32_e32 v29, v29
	s_nop 0
	v_add_f32_e32 v29, 1.0, v29
	v_log_f32_e32 v29, v29
	s_nop 0
	v_mul_f32_e32 v31, 0x3f317217, v29
	v_mov_b32_e32 v29, v31
	v_pk_add_f32 v[24:25], v[24:25], v[28:29] neg_lo:[0,1] neg_hi:[0,1]
	s_nop 0
	v_pk_mul_f32 v[84:85], v[24:25], s[50:51] op_sel_hi:[1,0]
	v_add_f32_e32 v25, v40, v26
	v_add_f32_e32 v24, v84, v30
	v_add_f32_e32 v28, v85, v24
	v_min_f32_e32 v24, 0, v25
	v_mul_f32_e64 v25, |v25|, s33
	v_exp_f32_e32 v25, v25
	s_nop 0
	v_add_f32_e32 v25, 1.0, v25
	v_log_f32_e32 v25, v25
	s_nop 0
	v_mul_f32_e32 v26, 0x3f317217, v25
	v_min_f32_e32 v25, 0, v27
	v_mul_f32_e64 v27, |v27|, s33
	v_exp_f32_e32 v27, v27
	s_nop 0
	v_add_f32_e32 v27, 1.0, v27
	v_log_f32_e32 v27, v27
	s_nop 0
	v_mul_f32_e32 v29, 0x3f317217, v27
	v_mov_b32_e32 v27, v29
	v_pk_add_f32 v[24:25], v[24:25], v[26:27] neg_lo:[0,1] neg_hi:[0,1]
	s_nop 0
	v_pk_mul_f32 v[86:87], v[24:25], s[50:51] op_sel_hi:[1,0]
	s_nop 0
	v_add_f32_e32 v24, v86, v28
	v_add_f32_e32 v79, v87, v24
	s_waitcnt vmcnt(5)
; __device__ __forceinline__ f32x4 mfma16(bf16x8 a, bf16x8 b, f32x4 c) { return __builtin_amdgcn_mfma_f32_16x16x32_bf16(a, b, c, 0, 0, 0); }
; template <int MODE> __device__ void mixer_gla(const Params& p, int l, int n, LAS unsigned char* lds) {
;     ...
;             for (int ef = 0; ef < 4; ++ef) { tot[ef] = 0.f;
; #pragma unroll
;                 for (int ks = 0; ks < 2; ++ks) { f32x4 la2[2];
; #pragma unroll
;                     for (int t2 = 0; t2 < 2; ++t2) { const f32x4 z = mfma16(lrf[2 * ks + t2], gwf[ef], zero4);
; #pragma unroll
;                         for (int r = 0; r < 4; ++r) { const float zz = z[r] + bgv[ef]; const float la = (fminf(zz, 0.f) - __logf(1.0f + __expf(-fabsf(zz)))) * (1.0f / 16.0f); la2[t2][r] = la; tot[ef] += la; } }
;                     laop[ef][ks] = pack8(la2[0], la2[1]); __builtin_amdgcn_sched_barrier(0); } }
;     ...
;             for (int ef = 0; ef < 4; ++ef) { float tt = tot[ef]; tt += __shfl_xor(tt, 16); tt += __shfl_xor(tt, 32);
;                 if (vh == 0 && q == 0) dec[((size_t)(dir * NCH + n) * 4 + h) * 64 + SIGC(ef, c)] = __expf(tt); }
	v_mfma_f32_16x16x32_bf16 v[64:67], v[12:15], v[16:19], 0
	v_mfma_f32_16x16x32_bf16 v[60:63], v[8:11], v[16:19], 0
	v_mfma_f32_16x16x32_bf16 v[56:59], v[36:39], v[16:19], 0
	v_mfma_f32_16x16x32_bf16 v[52:55], v[32:35], v[16:19], 0
	s_waitcnt vmcnt(3)
	v_mfma_f32_16x16x32_bf16 v[48:51], v[12:15], v[20:23], 0
	v_mfma_f32_16x16x32_bf16 v[40:43], v[8:11], v[20:23], 0
	v_mfma_f32_16x16x32_bf16 v[28:31], v[36:39], v[20:23], 0
	v_mfma_f32_16x16x32_bf16 v[24:27], v[32:35], v[20:23], 0
	s_waitcnt vmcnt(1)
	v_mfma_f32_16x16x32_bf16 v[20:23], v[12:15], v[44:47], 0
	v_mfma_f32_16x16x32_bf16 v[16:19], v[8:11], v[44:47], 0
	v_mfma_f32_16x16x32_bf16 v[12:15], v[36:39], v[44:47], 0
	v_mfma_f32_16x16x32_bf16 v[8:11], v[32:35], v[44:47], 0
	ds_bpermute_b32 v32, v91, v79
	s_add_i32 s8, s4, s12
	s_ashr_i32 s9, s8, 31
	s_lshl_b64 s[0:1], s[8:9], 10
	v_lshlrev_b32_e32 v176, 2, v90
	s_waitcnt lgkmcnt(0)
	v_add_f32_e32 v34, v79, v32
	ds_bpermute_b32 v35, v116, v34
	v_lshl_add_u64 v[32:33], v[94:95], 0, s[0:1]
	s_and_saveexec_b64 s[0:1], s[40:41]
	s_cbranch_execz .LBB0_340
	s_waitcnt lgkmcnt(0)
	v_add_f32_e32 v34, v34, v35
	v_mul_f32_e32 v34, 0x3fb8aa3b, v34
	v_exp_f32_e32 v36, v34
	v_lshl_add_u64 v[34:35], v[32:33], 0, v[176:177]
	global_store_dword v[34:35], v36, off
.LBB0_340:
	s_or_b64 exec, exec, s[0:1]
	s_waitcnt lgkmcnt(0)
	v_add_f32_e32 v35, v78, v64
	v_min_f32_e32 v34, 0, v35
	v_mul_f32_e64 v35, |v35|, s33
	v_exp_f32_e32 v35, v35
	v_add_f32_e32 v37, v78, v65
	v_add_f32_e32 v39, v78, v67
	v_add_f32_e32 v57, v78, v57
	v_add_f32_e32 v35, 1.0, v35
	v_add_f32_e32 v59, v78, v59
	v_add_f32_e32 v55, v78, v55
	v_log_f32_e32 v35, v35
	s_nop 0
	v_mul_f32_e32 v36, 0x3f317217, v35
	v_min_f32_e32 v35, 0, v37
	v_mul_f32_e64 v37, |v37|, s33
	v_exp_f32_e32 v37, v37
	s_nop 0
	v_add_f32_e32 v37, 1.0, v37
	v_log_f32_e32 v37, v37
	s_nop 0
	v_mul_f32_e32 v38, 0x3f317217, v37
	v_mov_b32_e32 v37, v38
	v_pk_add_f32 v[34:35], v[34:35], v[36:37] neg_lo:[0,1] neg_hi:[0,1]
	v_add_f32_e32 v37, v78, v66
	v_pk_mul_f32 v[34:35], v[34:35], s[50:51] op_sel_hi:[1,0]
	s_nop 0
	v_add_f32_e32 v36, 0, v34
	v_add_f32_e32 v44, v35, v36
	v_min_f32_e32 v36, 0, v37
	v_mul_f32_e64 v37, |v37|, s33
	v_exp_f32_e32 v37, v37
	s_nop 0
	v_add_f32_e32 v37, 1.0, v37
	v_log_f32_e32 v37, v37
	s_nop 0
	v_mul_f32_e32 v38, 0x3f317217, v37
	v_min_f32_e32 v37, 0, v39
	v_mul_f32_e64 v39, |v39|, s33
	v_exp_f32_e32 v39, v39
	s_nop 0
	v_add_f32_e32 v39, 1.0, v39
	v_log_f32_e32 v39, v39
	s_nop 0
	v_mul_f32_e32 v45, 0x3f317217, v39
	v_mov_b32_e32 v39, v45
	v_pk_add_f32 v[36:37], v[36:37], v[38:39] neg_lo:[0,1] neg_hi:[0,1]
	v_add_f32_e32 v39, v78, v60
	v_pk_mul_f32 v[36:37], v[36:37], s[50:51] op_sel_hi:[1,0]
	v_add_f32_e32 v45, v78, v61
	v_add_f32_e32 v38, v36, v44
	v_add_f32_e32 v46, v37, v38
	v_min_f32_e32 v38, 0, v39
	v_mul_f32_e64 v39, |v39|, s33
	v_exp_f32_e32 v39, v39
	s_nop 0
	v_add_f32_e32 v39, 1.0, v39
	v_log_f32_e32 v39, v39
	s_nop 0
	v_mul_f32_e32 v44, 0x3f317217, v39
	v_min_f32_e32 v39, 0, v45
	v_mul_f32_e64 v45, |v45|, s33
	v_exp_f32_e32 v45, v45
	s_nop 0
	v_add_f32_e32 v45, 1.0, v45
	v_log_f32_e32 v45, v45
	s_nop 0
	v_mul_f32_e32 v47, 0x3f317217, v45
	v_mov_b32_e32 v45, v47
	v_pk_add_f32 v[38:39], v[38:39], v[44:45] neg_lo:[0,1] neg_hi:[0,1]
	v_add_f32_e32 v45, v78, v62
	v_pk_mul_f32 v[38:39], v[38:39], s[50:51] op_sel_hi:[1,0]
	v_add_f32_e32 v47, v78, v63
	v_add_f32_e32 v44, v38, v46
	v_add_f32_e32 v60, v39, v44
	v_min_f32_e32 v44, 0, v45
	v_mul_f32_e64 v45, |v45|, s33
	v_exp_f32_e32 v45, v45
	s_nop 0
	v_add_f32_e32 v45, 1.0, v45
	v_log_f32_e32 v45, v45
	s_nop 0
	v_mul_f32_e32 v46, 0x3f317217, v45
	v_min_f32_e32 v45, 0, v47
	v_mul_f32_e64 v47, |v47|, s33
	v_exp_f32_e32 v47, v47
	s_nop 0
	v_add_f32_e32 v47, 1.0, v47
	v_log_f32_e32 v47, v47
	s_nop 0
	v_mul_f32_e32 v61, 0x3f317217, v47
	v_mov_b32_e32 v47, v61
	v_pk_add_f32 v[44:45], v[44:45], v[46:47] neg_lo:[0,1] neg_hi:[0,1]
	v_add_f32_e32 v47, v78, v56
	v_pk_mul_f32 v[44:45], v[44:45], s[50:51] op_sel_hi:[1,0]
	s_nop 0
	v_add_f32_e32 v46, v44, v60
	v_add_f32_e32 v60, v45, v46
	v_min_f32_e32 v46, 0, v47
	v_mul_f32_e64 v47, |v47|, s33
	v_exp_f32_e32 v47, v47
	s_nop 0
	v_add_f32_e32 v47, 1.0, v47
	v_log_f32_e32 v47, v47
	s_nop 0
	v_mul_f32_e32 v56, 0x3f317217, v47
	v_min_f32_e32 v47, 0, v57
	v_mul_f32_e64 v57, |v57|, s33
	v_exp_f32_e32 v57, v57
	s_nop 0
	v_add_f32_e32 v57, 1.0, v57
	v_log_f32_e32 v57, v57
	s_nop 0
	v_mul_f32_e32 v61, 0x3f317217, v57
	v_mov_b32_e32 v57, v61
	v_pk_add_f32 v[46:47], v[46:47], v[56:57] neg_lo:[0,1] neg_hi:[0,1]
	v_add_f32_e32 v57, v78, v58
	v_pk_mul_f32 v[46:47], v[46:47], s[50:51] op_sel_hi:[1,0]
	s_nop 0
	v_add_f32_e32 v56, v46, v60
	v_add_f32_e32 v60, v47, v56
	v_min_f32_e32 v56, 0, v57
	v_mul_f32_e64 v57, |v57|, s33
	v_exp_f32_e32 v57, v57
	s_nop 0
	v_add_f32_e32 v57, 1.0, v57
	v_log_f32_e32 v57, v57
	s_nop 0
	v_mul_f32_e32 v58, 0x3f317217, v57
	v_min_f32_e32 v57, 0, v59
	v_mul_f32_e64 v59, |v59|, s33
	v_exp_f32_e32 v59, v59
	s_nop 0
	v_add_f32_e32 v59, 1.0, v59
	v_log_f32_e32 v59, v59
	s_nop 0
	v_mul_f32_e32 v61, 0x3f317217, v59
	v_mov_b32_e32 v59, v61
	v_pk_add_f32 v[56:57], v[56:57], v[58:59] neg_lo:[0,1] neg_hi:[0,1]
	s_nop 0
	v_pk_mul_f32 v[56:57], v[56:57], s[50:51] op_sel_hi:[1,0]
	s_nop 0
	v_add_f32_e32 v58, v56, v60
	v_add_f32_e32 v60, v57, v58
	v_add_f32_e32 v58, v78, v52
	v_min_f32_e32 v52, 0, v58
	v_mul_f32_e64 v58, |v58|, s33
	v_exp_f32_e32 v58, v58
	s_nop 0
	v_add_f32_e32 v58, 1.0, v58
	v_log_f32_e32 v58, v58
	s_nop 0
	v_mul_f32_e32 v59, 0x3f317217, v58
	v_mov_b32_e32 v58, v59
	v_add_f32_e32 v59, v78, v53
	v_min_f32_e32 v53, 0, v59
	v_mul_f32_e64 v59, |v59|, s33
	v_exp_f32_e32 v59, v59
	s_nop 0
	v_add_f32_e32 v59, 1.0, v59
	v_log_f32_e32 v59, v59
	s_nop 0
	v_mul_f32_e32 v61, 0x3f317217, v59
	v_mov_b32_e32 v59, v61
	v_pk_add_f32 v[52:53], v[52:53], v[58:59] neg_lo:[0,1] neg_hi:[0,1]
	s_nop 0
	v_pk_mul_f32 v[58:59], v[52:53], s[50:51] op_sel_hi:[1,0]
	v_add_f32_e32 v53, v78, v54
	v_add_f32_e32 v52, v58, v60
	v_add_f32_e32 v60, v59, v52
	v_min_f32_e32 v52, 0, v53
	v_mul_f32_e64 v53, |v53|, s33
	v_exp_f32_e32 v53, v53
	s_nop 0
	v_add_f32_e32 v53, 1.0, v53
	v_log_f32_e32 v53, v53
	s_nop 0
	v_mul_f32_e32 v54, 0x3f317217, v53
	v_min_f32_e32 v53, 0, v55
	v_mul_f32_e64 v55, |v55|, s33
	v_exp_f32_e32 v55, v55
	s_nop 0
	v_add_f32_e32 v55, 1.0, v55
	v_log_f32_e32 v55, v55
	s_nop 0
	v_mul_f32_e32 v61, 0x3f317217, v55
	v_mov_b32_e32 v55, v61
	v_pk_add_f32 v[52:53], v[52:53], v[54:55] neg_lo:[0,1] neg_hi:[0,1]
	s_nop 0
	v_pk_mul_f32 v[64:65], v[52:53], s[50:51] op_sel_hi:[1,0]
	s_nop 0
	v_add_f32_e32 v52, v64, v60
	v_add_f32_e32 v52, v65, v52
	ds_bpermute_b32 v53, v91, v52
	s_waitcnt lgkmcnt(0)
	v_add_f32_e32 v52, v52, v53
	ds_bpermute_b32 v53, v116, v52
	s_and_saveexec_b64 s[0:1], s[40:41]
	s_cbranch_execz .LBB0_342
	s_waitcnt lgkmcnt(0)
	v_add_f32_e32 v52, v52, v53
	v_mul_f32_e32 v52, 0x3fb8aa3b, v52
	v_exp_f32_e32 v54, v52
	v_lshl_add_u64 v[52:53], v[32:33], 0, v[176:177]
	global_store_dword v[52:53], v54, off offset:16
; __device__ __forceinline__ f32x4 mfma16(bf16x8 a, bf16x8 b, f32x4 c) { return __builtin_amdgcn_mfma_f32_16x16x32_bf16(a, b, c, 0, 0, 0); }
; template <int MODE> __device__ void mixer_gla(const Params& p, int l, int n, LAS unsigned char* lds) {
;     ...
;             for (int ef = 0; ef < 4; ++ef) { tot[ef] = 0.f;
; #pragma unroll
;                 for (int ks = 0; ks < 2; ++ks) { f32x4 la2[2];
; #pragma unroll
;                     for (int t2 = 0; t2 < 2; ++t2) { const f32x4 z = mfma16(lrf[2 * ks + t2], gwf[ef], zero4);
; #pragma unroll
;                         for (int r = 0; r < 4; ++r) { const float zz = z[r] + bgv[ef]; const float la = (fminf(zz, 0.f) - __logf(1.0f + __expf(-fabsf(zz)))) * (1.0f / 16.0f); la2[t2][r] = la; tot[ef] += la; } }
;                     laop[ef][ks] = pack8(la2[0], la2[1]); __builtin_amdgcn_sched_barrier(0); } }
;     ...
;             for (int ef = 0; ef < 4; ++ef) { float tt = tot[ef]; tt += __shfl_xor(tt, 16); tt += __shfl_xor(tt, 32);
;                 if (vh == 0 && q == 0) dec[((size_t)(dir * NCH + n) * 4 + h) * 64 + SIGC(ef, c)] = __expf(tt); }
.LBB0_342:
	s_or_b64 exec, exec, s[0:1]
	v_add_f32_e32 v52, v77, v48
	v_min_f32_e32 v48, 0, v52
	v_mul_f32_e64 v52, |v52|, s33
	v_exp_f32_e32 v52, v52
	s_nop 0
	v_add_f32_e32 v52, 1.0, v52
	s_waitcnt lgkmcnt(0)
	s_nop 0
	v_log_f32_e32 v52, v52
	s_nop 0
	v_mul_f32_e32 v53, 0x3f317217, v52
	v_mov_b32_e32 v52, v53
	v_add_f32_e32 v53, v77, v49
	v_min_f32_e32 v49, 0, v53
	v_mul_f32_e64 v53, |v53|, s33
	v_exp_f32_e32 v53, v53
	s_nop 0
	v_add_f32_e32 v53, 1.0, v53
	v_log_f32_e32 v53, v53
	s_nop 0
	v_mul_f32_e32 v54, 0x3f317217, v53
	v_mov_b32_e32 v53, v54
	v_pk_add_f32 v[48:49], v[48:49], v[52:53] neg_lo:[0,1] neg_hi:[0,1]
	s_nop 0
	v_pk_mul_f32 v[48:49], v[48:49], s[50:51] op_sel_hi:[1,0]
	s_nop 0
	v_add_f32_e32 v52, 0, v48
	v_add_f32_e32 v54, v49, v52
	v_add_f32_e32 v52, v77, v50
	v_min_f32_e32 v50, 0, v52
	v_mul_f32_e64 v52, |v52|, s33
	v_exp_f32_e32 v52, v52
	s_nop 0
	v_add_f32_e32 v52, 1.0, v52
	v_log_f32_e32 v52, v52
	s_nop 0
	v_mul_f32_e32 v53, 0x3f317217, v52
	v_mov_b32_e32 v52, v53
	v_add_f32_e32 v53, v77, v51
	v_min_f32_e32 v51, 0, v53
	v_mul_f32_e64 v53, |v53|, s33
	v_exp_f32_e32 v53, v53
	s_nop 0
	v_add_f32_e32 v53, 1.0, v53
	v_log_f32_e32 v53, v53
	s_nop 0
	v_mul_f32_e32 v55, 0x3f317217, v53
	v_mov_b32_e32 v53, v55
	v_pk_add_f32 v[50:51], v[50:51], v[52:53] neg_lo:[0,1] neg_hi:[0,1]
	s_nop 0
	v_pk_mul_f32 v[50:51], v[50:51], s[50:51] op_sel_hi:[1,0]
	s_nop 0
	v_add_f32_e32 v52, v50, v54
	v_add_f32_e32 v54, v51, v52
	v_add_f32_e32 v52, v77, v40
	v_min_f32_e32 v40, 0, v52
	v_mul_f32_e64 v52, |v52|, s33
	v_exp_f32_e32 v52, v52
	s_nop 0
	v_add_f32_e32 v52, 1.0, v52
	v_log_f32_e32 v52, v52
	s_nop 0
	v_mul_f32_e32 v53, 0x3f317217, v52
	v_mov_b32_e32 v52, v53
	v_add_f32_e32 v53, v77, v41
	v_min_f32_e32 v41, 0, v53
	v_mul_f32_e64 v53, |v53|, s33
	v_exp_f32_e32 v53, v53
	s_nop 0
	v_add_f32_e32 v53, 1.0, v53
	v_log_f32_e32 v53, v53
	s_nop 0
	v_mul_f32_e32 v55, 0x3f317217, v53
	v_mov_b32_e32 v53, v55
	v_pk_add_f32 v[40:41], v[40:41], v[52:53] neg_lo:[0,1] neg_hi:[0,1]
	s_nop 0
	v_pk_mul_f32 v[40:41], v[40:41], s[50:51] op_sel_hi:[1,0]
	s_nop 0
	v_add_f32_e32 v52, v40, v54
	v_add_f32_e32 v54, v41, v52
	v_add_f32_e32 v52, v77, v42
	v_min_f32_e32 v42, 0, v52
	v_mul_f32_e64 v52, |v52|, s33
	v_exp_f32_e32 v52, v52
	s_nop 0
	v_add_f32_e32 v52, 1.0, v52
	v_log_f32_e32 v52, v52
	s_nop 0
	v_mul_f32_e32 v53, 0x3f317217, v52
	v_mov_b32_e32 v52, v53
	v_add_f32_e32 v53, v77, v43
	v_min_f32_e32 v43, 0, v53
	v_mul_f32_e64 v53, |v53|, s33
	v_exp_f32_e32 v53, v53
	s_nop 0
	v_add_f32_e32 v53, 1.0, v53
	v_log_f32_e32 v53, v53
	s_nop 0
	v_mul_f32_e32 v55, 0x3f317217, v53
	v_mov_b32_e32 v53, v55
	v_pk_add_f32 v[42:43], v[42:43], v[52:53] neg_lo:[0,1] neg_hi:[0,1]
	s_nop 0
	v_pk_mul_f32 v[42:43], v[42:43], s[50:51] op_sel_hi:[1,0]
	s_nop 0
	v_add_f32_e32 v52, v42, v54
	v_add_f32_e32 v54, v43, v52
	v_add_f32_e32 v52, v77, v28
	v_min_f32_e32 v28, 0, v52
	v_mul_f32_e64 v52, |v52|, s33
	v_exp_f32_e32 v52, v52
	s_nop 0
	v_add_f32_e32 v52, 1.0, v52
	v_log_f32_e32 v52, v52
	s_nop 0
	v_mul_f32_e32 v53, 0x3f317217, v52
	v_mov_b32_e32 v52, v53
	v_add_f32_e32 v53, v77, v29
	v_min_f32_e32 v29, 0, v53
	v_mul_f32_e64 v53, |v53|, s33
	v_exp_f32_e32 v53, v53
	s_nop 0
	v_add_f32_e32 v53, 1.0, v53
	v_log_f32_e32 v53, v53
	s_nop 0
	v_mul_f32_e32 v55, 0x3f317217, v53
	v_mov_b32_e32 v53, v55
	v_pk_add_f32 v[28:29], v[28:29], v[52:53] neg_lo:[0,1] neg_hi:[0,1]
	s_nop 0
	v_pk_mul_f32 v[28:29], v[28:29], s[50:51] op_sel_hi:[1,0]
	s_nop 0
	v_add_f32_e32 v52, v28, v54
	v_add_f32_e32 v54, v29, v52
	v_add_f32_e32 v52, v77, v30
	v_min_f32_e32 v30, 0, v52
	v_mul_f32_e64 v52, |v52|, s33
	v_exp_f32_e32 v52, v52
	s_nop 0
	v_add_f32_e32 v52, 1.0, v52
	v_log_f32_e32 v52, v52
	s_nop 0
	v_mul_f32_e32 v53, 0x3f317217, v52
	v_mov_b32_e32 v52, v53
	v_add_f32_e32 v53, v77, v31
	v_min_f32_e32 v31, 0, v53
	v_mul_f32_e64 v53, |v53|, s33
	v_exp_f32_e32 v53, v53
	s_nop 0
	v_add_f32_e32 v53, 1.0, v53
	v_log_f32_e32 v53, v53
	s_nop 0
	v_mul_f32_e32 v55, 0x3f317217, v53
	v_mov_b32_e32 v53, v55
	v_pk_add_f32 v[30:31], v[30:31], v[52:53] neg_lo:[0,1] neg_hi:[0,1]
	s_nop 0
	v_pk_mul_f32 v[30:31], v[30:31], s[50:51] op_sel_hi:[1,0]
	s_nop 0
	v_add_f32_e32 v52, v30, v54
	v_add_f32_e32 v54, v31, v52
	v_add_f32_e32 v52, v77, v24
	v_min_f32_e32 v24, 0, v52
	v_mul_f32_e64 v52, |v52|, s33
	v_exp_f32_e32 v52, v52
	s_nop 0
	v_add_f32_e32 v52, 1.0, v52
	v_log_f32_e32 v52, v52
	s_nop 0
	v_mul_f32_e32 v53, 0x3f317217, v52
	v_mov_b32_e32 v52, v53
	v_add_f32_e32 v53, v77, v25
	v_min_f32_e32 v25, 0, v53
	v_mul_f32_e64 v53, |v53|, s33
	v_exp_f32_e32 v53, v53
	s_nop 0
	v_add_f32_e32 v53, 1.0, v53
	v_log_f32_e32 v53, v53
	s_nop 0
	v_mul_f32_e32 v55, 0x3f317217, v53
	v_mov_b32_e32 v53, v55
	v_pk_add_f32 v[24:25], v[24:25], v[52:53] neg_lo:[0,1] neg_hi:[0,1]
	s_nop 0
	v_pk_mul_f32 v[24:25], v[24:25], s[50:51] op_sel_hi:[1,0]
	s_nop 0
	v_add_f32_e32 v52, v24, v54
	v_add_f32_e32 v54, v25, v52
	v_add_f32_e32 v52, v77, v26
	v_min_f32_e32 v26, 0, v52
	v_mul_f32_e64 v52, |v52|, s33
	v_exp_f32_e32 v52, v52
	s_nop 0
	v_add_f32_e32 v52, 1.0, v52
	v_log_f32_e32 v52, v52
	s_nop 0
	v_mul_f32_e32 v53, 0x3f317217, v52
	v_mov_b32_e32 v52, v53
	v_add_f32_e32 v53, v77, v27
	v_min_f32_e32 v27, 0, v53
	v_mul_f32_e64 v53, |v53|, s33
	v_exp_f32_e32 v53, v53
	s_nop 0
	v_add_f32_e32 v53, 1.0, v53
	v_log_f32_e32 v53, v53
	s_nop 0
	v_mul_f32_e32 v55, 0x3f317217, v53
	v_mov_b32_e32 v53, v55
	v_pk_add_f32 v[26:27], v[26:27], v[52:53] neg_lo:[0,1] neg_hi:[0,1]
	s_nop 0
	v_pk_mul_f32 v[26:27], v[26:27], s[50:51] op_sel_hi:[1,0]
	s_nop 0
	v_add_f32_e32 v52, v26, v54
	v_add_f32_e32 v52, v27, v52
	ds_bpermute_b32 v53, v91, v52
	s_waitcnt lgkmcnt(0)
	v_add_f32_e32 v52, v52, v53
	ds_bpermute_b32 v53, v116, v52
	s_and_saveexec_b64 s[0:1], s[40:41]
	s_cbranch_execz .LBB0_344
	s_waitcnt lgkmcnt(0)
	v_add_f32_e32 v52, v52, v53
	v_mul_f32_e32 v52, 0x3fb8aa3b, v52
	v_exp_f32_e32 v54, v52
	v_lshl_add_u64 v[52:53], v[32:33], 0, v[176:177]
	global_store_dword v[52:53], v54, off offset:128
; __device__ __forceinline__ f32x4 mfma16(bf16x8 a, bf16x8 b, f32x4 c) { return __builtin_amdgcn_mfma_f32_16x16x32_bf16(a, b, c, 0, 0, 0); }
; template <int MODE> __device__ void mixer_gla(const Params& p, int l, int n, LAS unsigned char* lds) {
;     ...
;             for (int ef = 0; ef < 4; ++ef) { tot[ef] = 0.f;
; #pragma unroll
;                 for (int ks = 0; ks < 2; ++ks) { f32x4 la2[2];
; #pragma unroll
;                     for (int t2 = 0; t2 < 2; ++t2) { const f32x4 z = mfma16(lrf[2 * ks + t2], gwf[ef], zero4);
; #pragma unroll
;                         for (int r = 0; r < 4; ++r) { const float zz = z[r] + bgv[ef]; const float la = (fminf(zz, 0.f) - __logf(1.0f + __expf(-fabsf(zz)))) * (1.0f / 16.0f); la2[t2][r] = la; tot[ef] += la; } }
;                     laop[ef][ks] = pack8(la2[0], la2[1]); __builtin_amdgcn_sched_barrier(0); } }
;     ...
;             for (int ef = 0; ef < 4; ++ef) { float tt = tot[ef]; tt += __shfl_xor(tt, 16); tt += __shfl_xor(tt, 32);
;                 if (vh == 0 && q == 0) dec[((size_t)(dir * NCH + n) * 4 + h) * 64 + SIGC(ef, c)] = __expf(tt); }
.LBB0_344:
	s_or_b64 exec, exec, s[0:1]
	s_waitcnt vmcnt(0)
	v_add_f32_e32 v52, v76, v20
	v_min_f32_e32 v20, 0, v52
	v_mul_f32_e64 v52, |v52|, s33
	v_exp_f32_e32 v52, v52
	s_nop 0
	v_add_f32_e32 v52, 1.0, v52
	s_waitcnt lgkmcnt(0)
	s_nop 0
	v_log_f32_e32 v52, v52
	s_nop 0
	v_mul_f32_e32 v53, 0x3f317217, v52
	v_mov_b32_e32 v52, v53
	v_add_f32_e32 v53, v76, v21
	v_min_f32_e32 v21, 0, v53
	v_mul_f32_e64 v53, |v53|, s33
	v_exp_f32_e32 v53, v53
	s_nop 0
	v_add_f32_e32 v53, 1.0, v53
	v_log_f32_e32 v53, v53
	s_nop 0
	v_mul_f32_e32 v54, 0x3f317217, v53
	v_mov_b32_e32 v53, v54
	v_pk_add_f32 v[20:21], v[20:21], v[52:53] neg_lo:[0,1] neg_hi:[0,1]
	s_nop 0
	v_pk_mul_f32 v[20:21], v[20:21], s[50:51] op_sel_hi:[1,0]
	s_nop 0
	v_add_f32_e32 v52, 0, v20
	v_add_f32_e32 v54, v21, v52
	v_add_f32_e32 v52, v76, v22
	v_min_f32_e32 v22, 0, v52
	v_mul_f32_e64 v52, |v52|, s33
	v_exp_f32_e32 v52, v52
	s_nop 0
	v_add_f32_e32 v52, 1.0, v52
	v_log_f32_e32 v52, v52
	s_nop 0
	v_mul_f32_e32 v53, 0x3f317217, v52
	v_mov_b32_e32 v52, v53
	v_add_f32_e32 v53, v76, v23
	v_min_f32_e32 v23, 0, v53
	v_mul_f32_e64 v53, |v53|, s33
	v_exp_f32_e32 v53, v53
	s_nop 0
	v_add_f32_e32 v53, 1.0, v53
	v_log_f32_e32 v53, v53
	s_nop 0
	v_mul_f32_e32 v55, 0x3f317217, v53
	v_mov_b32_e32 v53, v55
	v_pk_add_f32 v[22:23], v[22:23], v[52:53] neg_lo:[0,1] neg_hi:[0,1]
	s_nop 0
	v_pk_mul_f32 v[22:23], v[22:23], s[50:51] op_sel_hi:[1,0]
	s_nop 0
	v_add_f32_e32 v52, v22, v54
	v_add_f32_e32 v54, v23, v52
	v_add_f32_e32 v52, v76, v16
	v_min_f32_e32 v16, 0, v52
	v_mul_f32_e64 v52, |v52|, s33
	v_exp_f32_e32 v52, v52
	s_nop 0
	v_add_f32_e32 v52, 1.0, v52
	v_log_f32_e32 v52, v52
	s_nop 0
	v_mul_f32_e32 v53, 0x3f317217, v52
	v_mov_b32_e32 v52, v53
	v_add_f32_e32 v53, v76, v17
	v_min_f32_e32 v17, 0, v53
	v_mul_f32_e64 v53, |v53|, s33
	v_exp_f32_e32 v53, v53
	s_nop 0
	v_add_f32_e32 v53, 1.0, v53
	v_log_f32_e32 v53, v53
	s_nop 0
	v_mul_f32_e32 v55, 0x3f317217, v53
	v_mov_b32_e32 v53, v55
	v_pk_add_f32 v[16:17], v[16:17], v[52:53] neg_lo:[0,1] neg_hi:[0,1]
	s_nop 0
	v_pk_mul_f32 v[16:17], v[16:17], s[50:51] op_sel_hi:[1,0]
	s_nop 0
	v_add_f32_e32 v52, v16, v54
	v_add_f32_e32 v54, v17, v52
	v_add_f32_e32 v52, v76, v18
	v_min_f32_e32 v18, 0, v52
	v_mul_f32_e64 v52, |v52|, s33
	v_exp_f32_e32 v52, v52
	s_nop 0
	v_add_f32_e32 v52, 1.0, v52
	v_log_f32_e32 v52, v52
	s_nop 0
	v_mul_f32_e32 v53, 0x3f317217, v52
	v_mov_b32_e32 v52, v53
	v_add_f32_e32 v53, v76, v19
	v_min_f32_e32 v19, 0, v53
	v_mul_f32_e64 v53, |v53|, s33
	v_exp_f32_e32 v53, v53
	s_nop 0
	v_add_f32_e32 v53, 1.0, v53
	v_log_f32_e32 v53, v53
	s_nop 0
	v_mul_f32_e32 v55, 0x3f317217, v53
	v_mov_b32_e32 v53, v55
	v_pk_add_f32 v[18:19], v[18:19], v[52:53] neg_lo:[0,1] neg_hi:[0,1]
	s_nop 0
	v_pk_mul_f32 v[18:19], v[18:19], s[50:51] op_sel_hi:[1,0]
	s_nop 0
	v_add_f32_e32 v52, v18, v54
	v_add_f32_e32 v54, v19, v52
	v_add_f32_e32 v52, v76, v12
	v_min_f32_e32 v12, 0, v52
	v_mul_f32_e64 v52, |v52|, s33
	v_exp_f32_e32 v52, v52
	s_nop 0
	v_add_f32_e32 v52, 1.0, v52
	v_log_f32_e32 v52, v52
	s_nop 0
	v_mul_f32_e32 v53, 0x3f317217, v52
	v_mov_b32_e32 v52, v53
	v_add_f32_e32 v53, v76, v13
	v_min_f32_e32 v13, 0, v53
	v_mul_f32_e64 v53, |v53|, s33
	v_exp_f32_e32 v53, v53
	s_nop 0
	v_add_f32_e32 v53, 1.0, v53
	v_log_f32_e32 v53, v53
	s_nop 0
	v_mul_f32_e32 v55, 0x3f317217, v53
	v_mov_b32_e32 v53, v55
	v_pk_add_f32 v[12:13], v[12:13], v[52:53] neg_lo:[0,1] neg_hi:[0,1]
	s_nop 0
	v_pk_mul_f32 v[12:13], v[12:13], s[50:51] op_sel_hi:[1,0]
	s_nop 0
	v_add_f32_e32 v52, v12, v54
	v_add_f32_e32 v54, v13, v52
	v_add_f32_e32 v52, v76, v14
	v_min_f32_e32 v14, 0, v52
	v_mul_f32_e64 v52, |v52|, s33
	v_exp_f32_e32 v52, v52
	s_nop 0
	v_add_f32_e32 v52, 1.0, v52
	v_log_f32_e32 v52, v52
	s_nop 0
	v_mul_f32_e32 v53, 0x3f317217, v52
	v_mov_b32_e32 v52, v53
	v_add_f32_e32 v53, v76, v15
	v_min_f32_e32 v15, 0, v53
	v_mul_f32_e64 v53, |v53|, s33
	v_exp_f32_e32 v53, v53
	s_nop 0
	v_add_f32_e32 v53, 1.0, v53
	v_log_f32_e32 v53, v53
	s_nop 0
	v_mul_f32_e32 v55, 0x3f317217, v53
	v_mov_b32_e32 v53, v55
	v_pk_add_f32 v[14:15], v[14:15], v[52:53] neg_lo:[0,1] neg_hi:[0,1]
	s_nop 0
	v_pk_mul_f32 v[14:15], v[14:15], s[50:51] op_sel_hi:[1,0]
	s_nop 0
	v_add_f32_e32 v52, v14, v54
	v_add_f32_e32 v54, v15, v52
	v_add_f32_e32 v52, v76, v8
	v_min_f32_e32 v8, 0, v52
	v_mul_f32_e64 v52, |v52|, s33
	v_exp_f32_e32 v52, v52
	s_nop 0
	v_add_f32_e32 v52, 1.0, v52
	v_log_f32_e32 v52, v52
	s_nop 0
	v_mul_f32_e32 v53, 0x3f317217, v52
	v_mov_b32_e32 v52, v53
	v_add_f32_e32 v53, v76, v9
	v_min_f32_e32 v9, 0, v53
	v_mul_f32_e64 v53, |v53|, s33
	v_exp_f32_e32 v53, v53
	s_nop 0
	v_add_f32_e32 v53, 1.0, v53
	v_log_f32_e32 v53, v53
	s_nop 0
	v_mul_f32_e32 v55, 0x3f317217, v53
	v_mov_b32_e32 v53, v55
	v_pk_add_f32 v[8:9], v[8:9], v[52:53] neg_lo:[0,1] neg_hi:[0,1]
	s_nop 0
	v_pk_mul_f32 v[8:9], v[8:9], s[50:51] op_sel_hi:[1,0]
	s_nop 0
	v_add_f32_e32 v52, v8, v54
	v_add_f32_e32 v54, v9, v52
	v_add_f32_e32 v52, v76, v10
	v_min_f32_e32 v10, 0, v52
	v_mul_f32_e64 v52, |v52|, s33
	v_exp_f32_e32 v52, v52
	s_nop 0
	v_add_f32_e32 v52, 1.0, v52
	v_log_f32_e32 v52, v52
	s_nop 0
	v_mul_f32_e32 v53, 0x3f317217, v52
	v_mov_b32_e32 v52, v53
	v_add_f32_e32 v53, v76, v11
	v_min_f32_e32 v11, 0, v53
	v_mul_f32_e64 v53, |v53|, s33
	v_exp_f32_e32 v53, v53
	s_nop 0
	v_add_f32_e32 v53, 1.0, v53
	v_log_f32_e32 v53, v53
	s_nop 0
	v_mul_f32_e32 v55, 0x3f317217, v53
	v_mov_b32_e32 v53, v55
	v_pk_add_f32 v[10:11], v[10:11], v[52:53] neg_lo:[0,1] neg_hi:[0,1]
	s_nop 0
	v_pk_mul_f32 v[10:11], v[10:11], s[50:51] op_sel_hi:[1,0]
	s_nop 0
	v_add_f32_e32 v52, v10, v54
	v_add_f32_e32 v52, v11, v52
	ds_bpermute_b32 v53, v91, v52
	s_waitcnt lgkmcnt(0)
	v_add_f32_e32 v52, v52, v53
	ds_bpermute_b32 v53, v116, v52
	s_and_saveexec_b64 s[0:1], s[40:41]
	s_cbranch_execz .LBB0_329
	s_waitcnt lgkmcnt(0)
	v_add_f32_e32 v52, v52, v53
	v_mul_f32_e32 v52, 0x3fb8aa3b, v52
	v_exp_f32_e32 v52, v52
	v_lshl_add_u64 v[32:33], v[32:33], 0, v[176:177]
	global_store_dword v[32:33], v52, off offset:144
	s_branch .LBB0_329
